# plus residual-add epilogues issue all 16 residual loads up front; split-K combine loads batched by 12
# speedup vs baseline: 1.0031x; 1.0031x over previous
; #define LAS __attribute__((address_space(3)))
; __device__ __forceinline__ unsigned cvt_pk_bf16(float lo, float hi) { unsigned r; asm volatile("v_cvt_pk_bf16_f32 %0, %1, %2" : "=v"(r) : "v"(lo), "v"(hi)); return r; }
; #define EPR_LOAD(IT, BUF) do { const unsigned row_ = rb + 128 * ((IT) >> 2) + 16 * ((IT) & 3); _Pragma("unroll") for (int bj = 0; bj < 2; ++bj) \
;             xin[BUF][bj] = *(const u32x4*)(XG + (row_ * DM + cbase + bj * 128)); } while (0)
;     __device__ __forceinline__ void operator()(f32x4 (&acc)[2][2][4][2], const Unit& u, int ui, int wr, int wc, int fr, int fq, int lane, LAS unsigned char* lds) const {
;     ...
;         const unsigned cbase = (unsigned)(u.pn * 256 + wc * 32 + 8 * fq), rb = (unsigned)(u.pm * 256 + 64 * wr + fr);
;         LAS float* red = (LAS float*)(lds + EXTRA_OFF);
;         u32x4 xin[2][2];
;     ...
;         EPR_LOAD(0, 0);
; #pragma unroll
;         for (int it = 0; it < 8; ++it) {
;             if (it + 1 < 8) EPR_LOAD(it + 1, (it + 1) & 1);
;             __builtin_amdgcn_sched_barrier(0);
;             const int ai = it >> 2, m = it & 3;
;             const unsigned row = rb + 128 * ai + 16 * m;
;             float ss = 0.f;
; #pragma unroll
;             for (int bj = 0; bj < 2; ++bj) {
;                 const u32x4 xw = xin[it & 1][bj];
;                 f32x4 v0, v1;
;                 v0[0] = __builtin_bit_cast(float, xw.x << 16); v0[1] = __builtin_bit_cast(float, xw.x & 0xffff0000u); v0[2] = __builtin_bit_cast(float, xw.y << 16); v0[3] = __builtin_bit_cast(float, xw.y & 0xffff0000u);
;                 v1[0] = __builtin_bit_cast(float, xw.z << 16); v1[1] = __builtin_bit_cast(float, xw.z & 0xffff0000u); v1[2] = __builtin_bit_cast(float, xw.w << 16); v1[3] = __builtin_bit_cast(float, xw.w & 0xffff0000u);
;                 v0 += acc[ai][bj][m][0]; v1 += acc[ai][bj][m][1];
;                 ss += ((v0[0] * v0[0] + v0[1] * v0[1]) + (v0[2] * v0[2] + v0[3] * v0[3])) + ((v1[0] * v1[0] + v1[1] * v1[1]) + (v1[2] * v1[2] + v1[3] * v1[3]));
;                 u32x4 w; w.x = cvt_pk_bf16(v0[0], v0[1]); w.y = cvt_pk_bf16(v0[2], v0[3]); w.z = cvt_pk_bf16(v1[0], v1[1]); w.w = cvt_pk_bf16(v1[2], v1[3]);
;                 *(u32x4*)(XG + (row * DM + cbase + bj * 128)) = w;
;             }
;             ss += __shfl_xor(ss, 16); ss += __shfl_xor(ss, 32);
;             if (fq == 0) red[(128 * ai + 64 * wr + 16 * m + fr) * 4 + wc] = ss;
.LBB0_646:
	v_mov_b32_e32 v130, v142
	v_mov_b32_e32 v128, v140
	v_mov_b32_e32 v143, v141
	s_lshl_b32 s0, s40, 8
	s_lshl_b32 s1, s2, 18
	v_add_u32_e32 v160, s51, v128
	s_or_b32 s0, s0, s53
	v_lshlrev_b32_e32 v129, 3, v130
	v_lshlrev_b32_e32 v128, 10, v160
	s_add_i32 s0, s0, s1
	v_add3_u32 v188, s0, v129, v128
	v_add_u32_e32 v128, 0x80, v188
	v_mov_b32_e32 v129, v189
	v_lshl_add_u64 v[154:155], v[128:129], 1, s[8:9]
	v_add_u32_e32 v128, 0x4000, v188
	v_lshl_add_u64 v[136:137], v[128:129], 1, s[8:9]
	v_add_u32_e32 v128, 0x4080, v188
	v_lshl_add_u64 v[138:139], v[128:129], 1, s[8:9]
	v_lshl_add_u64 v[152:153], v[188:189], 1, s[8:9]
	v_cmp_eq_u32_e32 vcc, 0, v130
	global_load_dwordx4 v[132:135], v[136:137], off
	global_load_dwordx4 v[128:131], v[138:139], off
	global_load_dwordx4 v[144:147], v[152:153], off
	global_load_dwordx4 v[148:151], v[154:155], off
	s_mov_b32 s99, 0
	s_mov_b32 s98, 0x10000
	v_lshl_add_u64 v[186:187], v[152:153], 0, s[98:99]
	global_load_dwordx4 v[162:165], v[186:187], off
	global_load_dwordx4 v[166:169], v[186:187], off offset:256
	s_mov_b32 s98, 0x18000
	v_lshl_add_u64 v[186:187], v[152:153], 0, s[98:99]
	global_load_dwordx4 v[170:173], v[186:187], off
	global_load_dwordx4 v[174:177], v[186:187], off offset:256
	s_mov_b32 s98, 0x40000
	v_lshl_add_u64 v[186:187], v[152:153], 0, s[98:99]
	global_load_dwordx4 v[178:181], v[186:187], off
	global_load_dwordx4 v[182:185], v[186:187], off offset:256
	s_mov_b32 s98, 0x48000
	v_lshl_add_u64 v[186:187], v[152:153], 0, s[98:99]
	global_load_dwordx4 v[194:197], v[186:187], off
	global_load_dwordx4 v[198:201], v[186:187], off offset:256
	s_mov_b32 s98, 0x50000
	v_lshl_add_u64 v[186:187], v[152:153], 0, s[98:99]
	global_load_dwordx4 v[202:205], v[186:187], off
	global_load_dwordx4 v[212:215], v[186:187], off offset:256
	s_mov_b32 s98, 0x58000
	v_lshl_add_u64 v[186:187], v[152:153], 0, s[98:99]
	global_load_dwordx4 v[216:219], v[186:187], off
	global_load_dwordx4 v[220:223], v[186:187], off offset:256
	s_waitcnt vmcnt(12)
	v_lshlrev_b32_e32 v156, 16, v144
	v_and_b32_e32 v157, 0xffff0000, v144
	v_lshlrev_b32_e32 v144, 16, v145
	v_and_b32_e32 v145, 0xffff0000, v145
	v_lshlrev_b32_e32 v158, 16, v146
	v_and_b32_e32 v159, 0xffff0000, v146
	v_lshlrev_b32_e32 v146, 16, v147
	v_and_b32_e32 v147, 0xffff0000, v147
	v_pk_add_f32 v[126:127], v[126:127], v[144:145]
	v_pk_add_f32 v[124:125], v[124:125], v[156:157]
	v_pk_add_f32 v[144:145], v[122:123], v[146:147]
	v_pk_add_f32 v[122:123], v[120:121], v[158:159]
	v_mul_f32_e32 v120, v125, v125
	v_mul_f32_e32 v121, v127, v127
	v_fmac_f32_e32 v120, v124, v124
	v_fmac_f32_e32 v121, v126, v126
	v_add_f32_e32 v120, v120, v121
	v_mul_f32_e32 v121, v123, v123
	v_mul_f32_e32 v146, v145, v145
	v_fmac_f32_e32 v121, v122, v122
	v_fmac_f32_e32 v146, v144, v144
	v_add_f32_e32 v121, v121, v146
	v_add_f32_e32 v156, v120, v121
	v_cvt_pk_bf16_f32 v120, v124, v125
	v_cvt_pk_bf16_f32 v121, v126, v127
	v_lshlrev_b32_e32 v124, 16, v148
	v_and_b32_e32 v125, 0xffff0000, v148
	v_lshlrev_b32_e32 v126, 16, v149
	v_and_b32_e32 v127, 0xffff0000, v149
	v_lshlrev_b32_e32 v146, 16, v150
	v_and_b32_e32 v147, 0xffff0000, v150
	v_pk_add_f32 v[118:119], v[118:119], v[126:127]
	v_pk_add_f32 v[116:117], v[116:117], v[124:125]
	v_lshlrev_b32_e32 v148, 16, v151
	v_and_b32_e32 v149, 0xffff0000, v151
	v_pk_add_f32 v[146:147], v[112:113], v[146:147]
	v_mul_f32_e32 v112, v117, v117
	v_mul_f32_e32 v113, v119, v119
	v_pk_add_f32 v[148:149], v[114:115], v[148:149]
	v_fmac_f32_e32 v112, v116, v116
	v_fmac_f32_e32 v113, v118, v118
	v_add_f32_e32 v112, v112, v113
	v_mul_f32_e32 v113, v147, v147
	v_mul_f32_e32 v114, v149, v149
	v_fmac_f32_e32 v113, v146, v146
	v_fmac_f32_e32 v114, v148, v148
	v_add_f32_e32 v113, v113, v114
	v_and_b32_e32 v114, 64, v208
	v_add_f32_e32 v112, v112, v113
	v_xor_b32_e32 v113, 16, v208
	v_add_u32_e32 v124, 64, v114
	v_cmp_lt_i32_e64 s[4:5], v113, v124
	v_add_f32_e32 v112, v156, v112
	v_cvt_pk_bf16_f32 v122, v122, v123
	v_cvt_pk_bf16_f32 v123, v144, v145
	global_store_dwordx4 v[152:153], v[120:123], off
	v_cndmask_b32_e64 v113, v208, v113, s[4:5]
	v_lshlrev_b32_e32 v125, 2, v113
	ds_bpermute_b32 v113, v125, v112
	v_cvt_pk_bf16_f32 v114, v116, v117
	v_cvt_pk_bf16_f32 v115, v118, v119
	v_cvt_pk_bf16_f32 v116, v146, v147
	v_cvt_pk_bf16_f32 v117, v148, v149
	s_waitcnt lgkmcnt(0)
	v_add_f32_e32 v112, v112, v113
	v_xor_b32_e32 v113, 32, v208
	v_cmp_lt_i32_e64 s[4:5], v113, v124
	v_lshl_add_u32 v124, v160, 4, s64
	global_store_dwordx4 v[154:155], v[114:117], off
	v_cndmask_b32_e64 v113, v208, v113, s[4:5]
	v_lshlrev_b32_e32 v126, 2, v113
	ds_bpermute_b32 v113, v126, v112
	s_and_saveexec_b64 s[4:5], vcc
	s_cbranch_execz .LBB0_648
	s_waitcnt lgkmcnt(0)
	v_add_f32_e32 v112, v112, v113
	ds_write_b32 v124, v112
; __device__ __forceinline__ unsigned cvt_pk_bf16(float lo, float hi) { unsigned r; asm volatile("v_cvt_pk_bf16_f32 %0, %1, %2" : "=v"(r) : "v"(lo), "v"(hi)); return r; }
; #define EPR_LOAD(IT, BUF) do { const unsigned row_ = rb + 128 * ((IT) >> 2) + 16 * ((IT) & 3); _Pragma("unroll") for (int bj = 0; bj < 2; ++bj) \
;             xin[BUF][bj] = *(const u32x4*)(XG + (row_ * DM + cbase + bj * 128)); } while (0)
;     __device__ __forceinline__ void operator()(f32x4 (&acc)[2][2][4][2], const Unit& u, int ui, int wr, int wc, int fr, int fq, int lane, LAS unsigned char* lds) const {
;     ...
;         for (int it = 0; it < 8; ++it) {
;             if (it + 1 < 8) EPR_LOAD(it + 1, (it + 1) & 1);
;             __builtin_amdgcn_sched_barrier(0);
;             const int ai = it >> 2, m = it & 3;
;             const unsigned row = rb + 128 * ai + 16 * m;
;             float ss = 0.f;
; #pragma unroll
;             for (int bj = 0; bj < 2; ++bj) {
;                 const u32x4 xw = xin[it & 1][bj];
;                 f32x4 v0, v1;
;                 v0[0] = __builtin_bit_cast(float, xw.x << 16); v0[1] = __builtin_bit_cast(float, xw.x & 0xffff0000u); v0[2] = __builtin_bit_cast(float, xw.y << 16); v0[3] = __builtin_bit_cast(float, xw.y & 0xffff0000u);
;                 v1[0] = __builtin_bit_cast(float, xw.z << 16); v1[1] = __builtin_bit_cast(float, xw.z & 0xffff0000u); v1[2] = __builtin_bit_cast(float, xw.w << 16); v1[3] = __builtin_bit_cast(float, xw.w & 0xffff0000u);
;                 v0 += acc[ai][bj][m][0]; v1 += acc[ai][bj][m][1];
;                 ss += ((v0[0] * v0[0] + v0[1] * v0[1]) + (v0[2] * v0[2] + v0[3] * v0[3])) + ((v1[0] * v1[0] + v1[1] * v1[1]) + (v1[2] * v1[2] + v1[3] * v1[3]));
;                 u32x4 w; w.x = cvt_pk_bf16(v0[0], v0[1]); w.y = cvt_pk_bf16(v0[2], v0[3]); w.z = cvt_pk_bf16(v1[0], v1[1]); w.w = cvt_pk_bf16(v1[2], v1[3]);
;                 *(u32x4*)(XG + (row * DM + cbase + bj * 128)) = w;
;             }
;             ss += __shfl_xor(ss, 16); ss += __shfl_xor(ss, 32);
;             if (fq == 0) red[(128 * ai + 64 * wr + 16 * m + fr) * 4 + wc] = ss;
.LBB0_648:
	s_or_b64 exec, exec, s[4:5]
	v_add_u32_e32 v112, 0x8000, v188
	s_waitcnt lgkmcnt(0)
	v_mov_b32_e32 v113, v189
	v_lshl_add_u64 v[122:123], v[112:113], 1, s[8:9]
	v_add_u32_e32 v112, 0x8080, v188
	v_lshl_add_u64 v[120:121], v[112:113], 1, s[8:9]
	v_lshlrev_b32_e32 v144, 16, v132
	v_and_b32_e32 v145, 0xffff0000, v132
	v_lshlrev_b32_e32 v132, 16, v133
	v_and_b32_e32 v133, 0xffff0000, v133
	v_lshlrev_b32_e32 v146, 16, v134
	v_and_b32_e32 v147, 0xffff0000, v134
	v_lshlrev_b32_e32 v134, 16, v135
	v_and_b32_e32 v135, 0xffff0000, v135
	v_pk_add_f32 v[110:111], v[110:111], v[132:133]
	v_pk_add_f32 v[108:109], v[108:109], v[144:145]
	v_pk_add_f32 v[132:133], v[106:107], v[134:135]
	v_pk_add_f32 v[106:107], v[104:105], v[146:147]
	v_mul_f32_e32 v104, v109, v109
	v_mul_f32_e32 v105, v111, v111
	v_fmac_f32_e32 v104, v108, v108
	v_fmac_f32_e32 v105, v110, v110
	v_add_f32_e32 v104, v104, v105
	v_mul_f32_e32 v105, v107, v107
	v_mul_f32_e32 v127, v133, v133
	v_fmac_f32_e32 v105, v106, v106
	v_fmac_f32_e32 v127, v132, v132
	v_add_f32_e32 v105, v105, v127
	v_add_f32_e32 v127, v104, v105
	v_cvt_pk_bf16_f32 v104, v108, v109
	v_cvt_pk_bf16_f32 v105, v110, v111
	v_lshlrev_b32_e32 v108, 16, v128
	v_and_b32_e32 v109, 0xffff0000, v128
	v_lshlrev_b32_e32 v110, 16, v129
	v_and_b32_e32 v111, 0xffff0000, v129
	v_lshlrev_b32_e32 v128, 16, v130
	v_and_b32_e32 v129, 0xffff0000, v130
	v_pk_add_f32 v[102:103], v[102:103], v[110:111]
	v_pk_add_f32 v[100:101], v[100:101], v[108:109]
	v_lshlrev_b32_e32 v130, 16, v131
	v_and_b32_e32 v131, 0xffff0000, v131
	v_pk_add_f32 v[110:111], v[96:97], v[128:129]
	v_mul_f32_e32 v96, v101, v101
	v_mul_f32_e32 v97, v103, v103
	v_pk_add_f32 v[108:109], v[98:99], v[130:131]
	v_fmac_f32_e32 v96, v100, v100
	v_fmac_f32_e32 v97, v102, v102
	v_add_f32_e32 v96, v96, v97
	v_mul_f32_e32 v97, v111, v111
	v_mul_f32_e32 v98, v109, v109
	v_fmac_f32_e32 v97, v110, v110
	v_fmac_f32_e32 v98, v108, v108
	v_add_f32_e32 v97, v97, v98
	v_add_f32_e32 v96, v96, v97
	v_add_f32_e32 v96, v127, v96
	ds_bpermute_b32 v97, v125, v96
	v_cvt_pk_bf16_f32 v106, v106, v107
	v_cvt_pk_bf16_f32 v107, v132, v133
	global_store_dwordx4 v[136:137], v[104:107], off
	v_cvt_pk_bf16_f32 v98, v100, v101
	s_waitcnt lgkmcnt(0)
	v_add_f32_e32 v96, v96, v97
	ds_bpermute_b32 v97, v126, v96
	v_cvt_pk_bf16_f32 v99, v102, v103
	v_cvt_pk_bf16_f32 v100, v110, v111
	v_cvt_pk_bf16_f32 v101, v108, v109
	global_store_dwordx4 v[138:139], v[98:101], off
	s_and_saveexec_b64 s[4:5], vcc
	s_cbranch_execz .LBB0_650
	s_waitcnt lgkmcnt(0)
	v_add_f32_e32 v96, v96, v97
	ds_write_b32 v124, v96 offset:256
.LBB0_650:
	s_or_b64 exec, exec, s[4:5]
	v_add_u32_e32 v96, 0xc000, v188
	s_waitcnt lgkmcnt(0)
	v_mov_b32_e32 v97, v189
	v_lshl_add_u64 v[106:107], v[96:97], 1, s[8:9]
	v_add_u32_e32 v96, 0xc080, v188
	v_lshl_add_u64 v[104:105], v[96:97], 1, s[8:9]
	s_waitcnt vmcnt(15)
	v_lshlrev_b32_e32 v108, 16, v162
	v_and_b32_e32 v109, 0xffff0000, v162
	v_lshlrev_b32_e32 v110, 16, v163
	v_and_b32_e32 v111, 0xffff0000, v163
	v_lshlrev_b32_e32 v116, 16, v164
	v_and_b32_e32 v117, 0xffff0000, v164
	v_lshlrev_b32_e32 v118, 16, v165
	v_and_b32_e32 v119, 0xffff0000, v165
	v_pk_add_f32 v[94:95], v[94:95], v[110:111]
	v_pk_add_f32 v[92:93], v[92:93], v[108:109]
	v_pk_add_f32 v[108:109], v[90:91], v[118:119]
	v_pk_add_f32 v[90:91], v[88:89], v[116:117]
	v_mul_f32_e32 v88, v93, v93
	v_mul_f32_e32 v89, v95, v95
	v_fmac_f32_e32 v88, v92, v92
	v_fmac_f32_e32 v89, v94, v94
	v_add_f32_e32 v88, v88, v89
	v_mul_f32_e32 v89, v91, v91
	v_mul_f32_e32 v110, v109, v109
	v_fmac_f32_e32 v89, v90, v90
	v_fmac_f32_e32 v110, v108, v108
	v_add_f32_e32 v89, v89, v110
	v_add_f32_e32 v116, v88, v89
	v_cvt_pk_bf16_f32 v88, v92, v93
	v_cvt_pk_bf16_f32 v89, v94, v95
	s_waitcnt vmcnt(14)
	v_lshlrev_b32_e32 v92, 16, v166
	v_and_b32_e32 v93, 0xffff0000, v166
	v_lshlrev_b32_e32 v94, 16, v167
	v_and_b32_e32 v95, 0xffff0000, v167
	v_lshlrev_b32_e32 v110, 16, v168
	v_and_b32_e32 v111, 0xffff0000, v168
	v_pk_add_f32 v[86:87], v[86:87], v[94:95]
	v_pk_add_f32 v[84:85], v[84:85], v[92:93]
	v_lshlrev_b32_e32 v112, 16, v169
	v_and_b32_e32 v113, 0xffff0000, v169
	v_pk_add_f32 v[94:95], v[80:81], v[110:111]
	v_mul_f32_e32 v80, v85, v85
	v_mul_f32_e32 v81, v87, v87
	v_pk_add_f32 v[92:93], v[82:83], v[112:113]
	v_fmac_f32_e32 v80, v84, v84
	v_fmac_f32_e32 v81, v86, v86
	v_add_f32_e32 v80, v80, v81
	v_mul_f32_e32 v81, v95, v95
	v_mul_f32_e32 v82, v93, v93
	v_fmac_f32_e32 v81, v94, v94
	v_fmac_f32_e32 v82, v92, v92
	v_add_f32_e32 v81, v81, v82
	v_add_f32_e32 v80, v80, v81
	v_add_f32_e32 v80, v116, v80
	ds_bpermute_b32 v81, v125, v80
	v_cvt_pk_bf16_f32 v90, v90, v91
	v_cvt_pk_bf16_f32 v91, v108, v109
	global_store_dwordx4 v[122:123], v[88:91], off
	v_cvt_pk_bf16_f32 v82, v84, v85
	s_waitcnt lgkmcnt(0)
	v_add_f32_e32 v80, v80, v81
	ds_bpermute_b32 v81, v126, v80
	v_cvt_pk_bf16_f32 v83, v86, v87
	v_cvt_pk_bf16_f32 v84, v94, v95
	v_cvt_pk_bf16_f32 v85, v92, v93
	global_store_dwordx4 v[120:121], v[82:85], off
	s_and_saveexec_b64 s[4:5], vcc
	s_cbranch_execz .LBB0_652
	s_waitcnt lgkmcnt(0)
	v_add_f32_e32 v80, v80, v81
	ds_write_b32 v124, v80 offset:512
; __device__ __forceinline__ unsigned cvt_pk_bf16(float lo, float hi) { unsigned r; asm volatile("v_cvt_pk_bf16_f32 %0, %1, %2" : "=v"(r) : "v"(lo), "v"(hi)); return r; }
; #define EPR_LOAD(IT, BUF) do { const unsigned row_ = rb + 128 * ((IT) >> 2) + 16 * ((IT) & 3); _Pragma("unroll") for (int bj = 0; bj < 2; ++bj) \
;             xin[BUF][bj] = *(const u32x4*)(XG + (row_ * DM + cbase + bj * 128)); } while (0)
;     __device__ __forceinline__ void operator()(f32x4 (&acc)[2][2][4][2], const Unit& u, int ui, int wr, int wc, int fr, int fq, int lane, LAS unsigned char* lds) const {
;     ...
;         for (int it = 0; it < 8; ++it) {
;             if (it + 1 < 8) EPR_LOAD(it + 1, (it + 1) & 1);
;             __builtin_amdgcn_sched_barrier(0);
;             const int ai = it >> 2, m = it & 3;
;             const unsigned row = rb + 128 * ai + 16 * m;
;             float ss = 0.f;
; #pragma unroll
;             for (int bj = 0; bj < 2; ++bj) {
;                 const u32x4 xw = xin[it & 1][bj];
;                 f32x4 v0, v1;
;                 v0[0] = __builtin_bit_cast(float, xw.x << 16); v0[1] = __builtin_bit_cast(float, xw.x & 0xffff0000u); v0[2] = __builtin_bit_cast(float, xw.y << 16); v0[3] = __builtin_bit_cast(float, xw.y & 0xffff0000u);
;                 v1[0] = __builtin_bit_cast(float, xw.z << 16); v1[1] = __builtin_bit_cast(float, xw.z & 0xffff0000u); v1[2] = __builtin_bit_cast(float, xw.w << 16); v1[3] = __builtin_bit_cast(float, xw.w & 0xffff0000u);
;                 v0 += acc[ai][bj][m][0]; v1 += acc[ai][bj][m][1];
;                 ss += ((v0[0] * v0[0] + v0[1] * v0[1]) + (v0[2] * v0[2] + v0[3] * v0[3])) + ((v1[0] * v1[0] + v1[1] * v1[1]) + (v1[2] * v1[2] + v1[3] * v1[3]));
;                 u32x4 w; w.x = cvt_pk_bf16(v0[0], v0[1]); w.y = cvt_pk_bf16(v0[2], v0[3]); w.z = cvt_pk_bf16(v1[0], v1[1]); w.w = cvt_pk_bf16(v1[2], v1[3]);
;                 *(u32x4*)(XG + (row * DM + cbase + bj * 128)) = w;
;             }
;             ss += __shfl_xor(ss, 16); ss += __shfl_xor(ss, 32);
;             if (fq == 0) red[(128 * ai + 64 * wr + 16 * m + fr) * 4 + wc] = ss;
.LBB0_652:
	s_or_b64 exec, exec, s[4:5]
	v_add_u32_e32 v80, 0x20000, v188
	s_waitcnt lgkmcnt(0)
	v_mov_b32_e32 v81, v189
	v_lshl_add_u64 v[90:91], v[80:81], 1, s[8:9]
	v_add_u32_e32 v80, 0x20080, v188
	v_lshl_add_u64 v[88:89], v[80:81], 1, s[8:9]
	s_waitcnt vmcnt(15)
	v_lshlrev_b32_e32 v92, 16, v170
	v_and_b32_e32 v93, 0xffff0000, v170
	v_lshlrev_b32_e32 v94, 16, v171
	v_and_b32_e32 v95, 0xffff0000, v171
	v_lshlrev_b32_e32 v100, 16, v172
	v_and_b32_e32 v101, 0xffff0000, v172
	v_lshlrev_b32_e32 v102, 16, v173
	v_and_b32_e32 v103, 0xffff0000, v173
	v_pk_add_f32 v[78:79], v[78:79], v[94:95]
	v_pk_add_f32 v[76:77], v[76:77], v[92:93]
	v_pk_add_f32 v[92:93], v[74:75], v[102:103]
	v_pk_add_f32 v[74:75], v[72:73], v[100:101]
	v_mul_f32_e32 v72, v77, v77
	v_mul_f32_e32 v73, v79, v79
	v_fmac_f32_e32 v72, v76, v76
	v_fmac_f32_e32 v73, v78, v78
	v_add_f32_e32 v72, v72, v73
	v_mul_f32_e32 v73, v75, v75
	v_mul_f32_e32 v94, v93, v93
	v_fmac_f32_e32 v73, v74, v74
	v_fmac_f32_e32 v94, v92, v92
	v_add_f32_e32 v73, v73, v94
	v_add_f32_e32 v100, v72, v73
	v_cvt_pk_bf16_f32 v72, v76, v77
	v_cvt_pk_bf16_f32 v73, v78, v79
	s_waitcnt vmcnt(14)
	v_lshlrev_b32_e32 v76, 16, v174
	v_and_b32_e32 v77, 0xffff0000, v174
	v_lshlrev_b32_e32 v78, 16, v175
	v_and_b32_e32 v79, 0xffff0000, v175
	v_lshlrev_b32_e32 v94, 16, v176
	v_and_b32_e32 v95, 0xffff0000, v176
	v_pk_add_f32 v[70:71], v[70:71], v[78:79]
	v_pk_add_f32 v[68:69], v[68:69], v[76:77]
	v_lshlrev_b32_e32 v96, 16, v177
	v_and_b32_e32 v97, 0xffff0000, v177
	v_pk_add_f32 v[78:79], v[64:65], v[94:95]
	v_mul_f32_e32 v64, v69, v69
	v_mul_f32_e32 v65, v71, v71
	v_pk_add_f32 v[76:77], v[66:67], v[96:97]
	v_fmac_f32_e32 v64, v68, v68
	v_fmac_f32_e32 v65, v70, v70
	v_add_f32_e32 v64, v64, v65
	v_mul_f32_e32 v65, v79, v79
	v_mul_f32_e32 v66, v77, v77
	v_fmac_f32_e32 v65, v78, v78
	v_fmac_f32_e32 v66, v76, v76
	v_add_f32_e32 v65, v65, v66
	v_add_f32_e32 v64, v64, v65
	v_add_f32_e32 v64, v100, v64
	ds_bpermute_b32 v65, v125, v64
	v_cvt_pk_bf16_f32 v74, v74, v75
	v_cvt_pk_bf16_f32 v75, v92, v93
	global_store_dwordx4 v[106:107], v[72:75], off
	v_cvt_pk_bf16_f32 v66, v68, v69
	s_waitcnt lgkmcnt(0)
	v_add_f32_e32 v64, v64, v65
	ds_bpermute_b32 v65, v126, v64
	v_cvt_pk_bf16_f32 v67, v70, v71
	v_cvt_pk_bf16_f32 v68, v78, v79
	v_cvt_pk_bf16_f32 v69, v76, v77
	global_store_dwordx4 v[104:105], v[66:69], off
	s_and_saveexec_b64 s[4:5], vcc
	s_cbranch_execz .LBB0_654
	s_waitcnt lgkmcnt(0)
	v_add_f32_e32 v64, v64, v65
	ds_write_b32 v124, v64 offset:768
.LBB0_654:
	s_or_b64 exec, exec, s[4:5]
	v_add_u32_e32 v64, 0x24000, v188
	s_waitcnt lgkmcnt(0)
	v_mov_b32_e32 v65, v189
	v_lshl_add_u64 v[74:75], v[64:65], 1, s[8:9]
	v_add_u32_e32 v64, 0x24080, v188
	v_lshl_add_u64 v[72:73], v[64:65], 1, s[8:9]
	s_waitcnt vmcnt(15)
	v_lshlrev_b32_e32 v76, 16, v178
	v_and_b32_e32 v77, 0xffff0000, v178
	v_lshlrev_b32_e32 v78, 16, v179
	v_and_b32_e32 v79, 0xffff0000, v179
	v_lshlrev_b32_e32 v84, 16, v180
	v_and_b32_e32 v85, 0xffff0000, v180
	v_lshlrev_b32_e32 v86, 16, v181
	v_and_b32_e32 v87, 0xffff0000, v181
	v_pk_add_f32 v[62:63], v[62:63], v[78:79]
	v_pk_add_f32 v[60:61], v[60:61], v[76:77]
	v_pk_add_f32 v[76:77], v[58:59], v[86:87]
	v_pk_add_f32 v[58:59], v[56:57], v[84:85]
	v_mul_f32_e32 v56, v61, v61
	v_mul_f32_e32 v57, v63, v63
	v_fmac_f32_e32 v56, v60, v60
	v_fmac_f32_e32 v57, v62, v62
	v_add_f32_e32 v56, v56, v57
	v_mul_f32_e32 v57, v59, v59
	v_mul_f32_e32 v78, v77, v77
	v_fmac_f32_e32 v57, v58, v58
	v_fmac_f32_e32 v78, v76, v76
	v_add_f32_e32 v57, v57, v78
	v_add_f32_e32 v84, v56, v57
	v_cvt_pk_bf16_f32 v56, v60, v61
	v_cvt_pk_bf16_f32 v57, v62, v63
	s_waitcnt vmcnt(14)
	v_lshlrev_b32_e32 v60, 16, v182
	v_and_b32_e32 v61, 0xffff0000, v182
	v_lshlrev_b32_e32 v62, 16, v183
	v_and_b32_e32 v63, 0xffff0000, v183
	v_lshlrev_b32_e32 v78, 16, v184
	v_and_b32_e32 v79, 0xffff0000, v184
	v_pk_add_f32 v[54:55], v[54:55], v[62:63]
	v_pk_add_f32 v[52:53], v[52:53], v[60:61]
	v_lshlrev_b32_e32 v80, 16, v185
	v_and_b32_e32 v81, 0xffff0000, v185
	v_pk_add_f32 v[62:63], v[48:49], v[78:79]
	v_mul_f32_e32 v48, v53, v53
	v_mul_f32_e32 v49, v55, v55
	v_pk_add_f32 v[60:61], v[50:51], v[80:81]
	v_fmac_f32_e32 v48, v52, v52
	v_fmac_f32_e32 v49, v54, v54
	v_add_f32_e32 v48, v48, v49
	v_mul_f32_e32 v49, v63, v63
	v_mul_f32_e32 v50, v61, v61
	v_fmac_f32_e32 v49, v62, v62
	v_fmac_f32_e32 v50, v60, v60
	v_add_f32_e32 v49, v49, v50
	v_add_f32_e32 v48, v48, v49
	v_add_f32_e32 v48, v84, v48
	ds_bpermute_b32 v49, v125, v48
	v_cvt_pk_bf16_f32 v58, v58, v59
	v_cvt_pk_bf16_f32 v59, v76, v77
	global_store_dwordx4 v[90:91], v[56:59], off
	v_cvt_pk_bf16_f32 v50, v52, v53
	s_waitcnt lgkmcnt(0)
	v_add_f32_e32 v48, v48, v49
	ds_bpermute_b32 v49, v126, v48
	v_cvt_pk_bf16_f32 v51, v54, v55
	v_cvt_pk_bf16_f32 v52, v62, v63
	v_cvt_pk_bf16_f32 v53, v60, v61
	global_store_dwordx4 v[88:89], v[50:53], off
	s_and_saveexec_b64 s[4:5], vcc
	s_cbranch_execz .LBB0_656
	s_waitcnt lgkmcnt(0)
	v_add_f32_e32 v48, v48, v49
	ds_write_b32 v124, v48 offset:2048
; __device__ __forceinline__ unsigned cvt_pk_bf16(float lo, float hi) { unsigned r; asm volatile("v_cvt_pk_bf16_f32 %0, %1, %2" : "=v"(r) : "v"(lo), "v"(hi)); return r; }
; #define EPR_LOAD(IT, BUF) do { const unsigned row_ = rb + 128 * ((IT) >> 2) + 16 * ((IT) & 3); _Pragma("unroll") for (int bj = 0; bj < 2; ++bj) \
;             xin[BUF][bj] = *(const u32x4*)(XG + (row_ * DM + cbase + bj * 128)); } while (0)
;     __device__ __forceinline__ void operator()(f32x4 (&acc)[2][2][4][2], const Unit& u, int ui, int wr, int wc, int fr, int fq, int lane, LAS unsigned char* lds) const {
;     ...
;         for (int it = 0; it < 8; ++it) {
;             if (it + 1 < 8) EPR_LOAD(it + 1, (it + 1) & 1);
;             __builtin_amdgcn_sched_barrier(0);
;             const int ai = it >> 2, m = it & 3;
;             const unsigned row = rb + 128 * ai + 16 * m;
;             float ss = 0.f;
; #pragma unroll
;             for (int bj = 0; bj < 2; ++bj) {
;                 const u32x4 xw = xin[it & 1][bj];
;                 f32x4 v0, v1;
;                 v0[0] = __builtin_bit_cast(float, xw.x << 16); v0[1] = __builtin_bit_cast(float, xw.x & 0xffff0000u); v0[2] = __builtin_bit_cast(float, xw.y << 16); v0[3] = __builtin_bit_cast(float, xw.y & 0xffff0000u);
;                 v1[0] = __builtin_bit_cast(float, xw.z << 16); v1[1] = __builtin_bit_cast(float, xw.z & 0xffff0000u); v1[2] = __builtin_bit_cast(float, xw.w << 16); v1[3] = __builtin_bit_cast(float, xw.w & 0xffff0000u);
;                 v0 += acc[ai][bj][m][0]; v1 += acc[ai][bj][m][1];
;                 ss += ((v0[0] * v0[0] + v0[1] * v0[1]) + (v0[2] * v0[2] + v0[3] * v0[3])) + ((v1[0] * v1[0] + v1[1] * v1[1]) + (v1[2] * v1[2] + v1[3] * v1[3]));
;                 u32x4 w; w.x = cvt_pk_bf16(v0[0], v0[1]); w.y = cvt_pk_bf16(v0[2], v0[3]); w.z = cvt_pk_bf16(v1[0], v1[1]); w.w = cvt_pk_bf16(v1[2], v1[3]);
;                 *(u32x4*)(XG + (row * DM + cbase + bj * 128)) = w;
;             }
;             ss += __shfl_xor(ss, 16); ss += __shfl_xor(ss, 32);
;             if (fq == 0) red[(128 * ai + 64 * wr + 16 * m + fr) * 4 + wc] = ss;
.LBB0_656:
	s_or_b64 exec, exec, s[4:5]
	v_add_u32_e32 v48, 0x28000, v188
	s_waitcnt lgkmcnt(0)
	v_mov_b32_e32 v49, v189
	v_lshl_add_u64 v[58:59], v[48:49], 1, s[8:9]
	v_add_u32_e32 v48, 0x28080, v188
	v_lshl_add_u64 v[56:57], v[48:49], 1, s[8:9]
	s_waitcnt vmcnt(15)
	v_lshlrev_b32_e32 v60, 16, v194
	v_and_b32_e32 v61, 0xffff0000, v194
	v_lshlrev_b32_e32 v62, 16, v195
	v_and_b32_e32 v63, 0xffff0000, v195
	v_lshlrev_b32_e32 v68, 16, v196
	v_and_b32_e32 v69, 0xffff0000, v196
	v_lshlrev_b32_e32 v70, 16, v197
	v_and_b32_e32 v71, 0xffff0000, v197
	v_pk_add_f32 v[46:47], v[46:47], v[62:63]
	v_pk_add_f32 v[44:45], v[44:45], v[60:61]
	v_pk_add_f32 v[60:61], v[42:43], v[70:71]
	v_pk_add_f32 v[42:43], v[40:41], v[68:69]
	v_mul_f32_e32 v40, v45, v45
	v_mul_f32_e32 v41, v47, v47
	v_fmac_f32_e32 v40, v44, v44
	v_fmac_f32_e32 v41, v46, v46
	v_add_f32_e32 v40, v40, v41
	v_mul_f32_e32 v41, v43, v43
	v_mul_f32_e32 v62, v61, v61
	v_fmac_f32_e32 v41, v42, v42
	v_fmac_f32_e32 v62, v60, v60
	v_add_f32_e32 v41, v41, v62
	v_add_f32_e32 v68, v40, v41
	v_cvt_pk_bf16_f32 v40, v44, v45
	v_cvt_pk_bf16_f32 v41, v46, v47
	s_waitcnt vmcnt(14)
	v_lshlrev_b32_e32 v44, 16, v198
	v_and_b32_e32 v45, 0xffff0000, v198
	v_lshlrev_b32_e32 v46, 16, v199
	v_and_b32_e32 v47, 0xffff0000, v199
	v_lshlrev_b32_e32 v62, 16, v200
	v_and_b32_e32 v63, 0xffff0000, v200
	v_pk_add_f32 v[38:39], v[38:39], v[46:47]
	v_pk_add_f32 v[36:37], v[36:37], v[44:45]
	v_lshlrev_b32_e32 v64, 16, v201
	v_and_b32_e32 v65, 0xffff0000, v201
	v_pk_add_f32 v[46:47], v[32:33], v[62:63]
	v_mul_f32_e32 v32, v37, v37
	v_mul_f32_e32 v33, v39, v39
	v_pk_add_f32 v[44:45], v[34:35], v[64:65]
	v_fmac_f32_e32 v32, v36, v36
	v_fmac_f32_e32 v33, v38, v38
	v_add_f32_e32 v32, v32, v33
	v_mul_f32_e32 v33, v47, v47
	v_mul_f32_e32 v34, v45, v45
	v_fmac_f32_e32 v33, v46, v46
	v_fmac_f32_e32 v34, v44, v44
	v_add_f32_e32 v33, v33, v34
	v_add_f32_e32 v32, v32, v33
	v_add_f32_e32 v32, v68, v32
	ds_bpermute_b32 v33, v125, v32
	v_cvt_pk_bf16_f32 v42, v42, v43
	v_cvt_pk_bf16_f32 v43, v60, v61
	global_store_dwordx4 v[74:75], v[40:43], off
	v_cvt_pk_bf16_f32 v34, v36, v37
	s_waitcnt lgkmcnt(0)
	v_add_f32_e32 v32, v32, v33
	ds_bpermute_b32 v33, v126, v32
	v_cvt_pk_bf16_f32 v35, v38, v39
	v_cvt_pk_bf16_f32 v36, v46, v47
	v_cvt_pk_bf16_f32 v37, v44, v45
	global_store_dwordx4 v[72:73], v[34:37], off
	s_and_saveexec_b64 s[4:5], vcc
	s_cbranch_execz .LBB0_658
	s_waitcnt lgkmcnt(0)
	v_add_f32_e32 v32, v32, v33
	ds_write_b32 v124, v32 offset:2304
; __device__ __forceinline__ unsigned cvt_pk_bf16(float lo, float hi) { unsigned r; asm volatile("v_cvt_pk_bf16_f32 %0, %1, %2" : "=v"(r) : "v"(lo), "v"(hi)); return r; }
; #define EPR_LOAD(IT, BUF) do { const unsigned row_ = rb + 128 * ((IT) >> 2) + 16 * ((IT) & 3); _Pragma("unroll") for (int bj = 0; bj < 2; ++bj) \
;             xin[BUF][bj] = *(const u32x4*)(XG + (row_ * DM + cbase + bj * 128)); } while (0)
;     __device__ __forceinline__ void operator()(f32x4 (&acc)[2][2][4][2], const Unit& u, int ui, int wr, int wc, int fr, int fq, int lane, LAS unsigned char* lds) const {
;     ...
;         for (int it = 0; it < 8; ++it) {
;             if (it + 1 < 8) EPR_LOAD(it + 1, (it + 1) & 1);
;             __builtin_amdgcn_sched_barrier(0);
;             const int ai = it >> 2, m = it & 3;
;             const unsigned row = rb + 128 * ai + 16 * m;
;             float ss = 0.f;
; #pragma unroll
;             for (int bj = 0; bj < 2; ++bj) {
;                 const u32x4 xw = xin[it & 1][bj];
;                 f32x4 v0, v1;
;                 v0[0] = __builtin_bit_cast(float, xw.x << 16); v0[1] = __builtin_bit_cast(float, xw.x & 0xffff0000u); v0[2] = __builtin_bit_cast(float, xw.y << 16); v0[3] = __builtin_bit_cast(float, xw.y & 0xffff0000u);
;                 v1[0] = __builtin_bit_cast(float, xw.z << 16); v1[1] = __builtin_bit_cast(float, xw.z & 0xffff0000u); v1[2] = __builtin_bit_cast(float, xw.w << 16); v1[3] = __builtin_bit_cast(float, xw.w & 0xffff0000u);
;                 v0 += acc[ai][bj][m][0]; v1 += acc[ai][bj][m][1];
;                 ss += ((v0[0] * v0[0] + v0[1] * v0[1]) + (v0[2] * v0[2] + v0[3] * v0[3])) + ((v1[0] * v1[0] + v1[1] * v1[1]) + (v1[2] * v1[2] + v1[3] * v1[3]));
;                 u32x4 w; w.x = cvt_pk_bf16(v0[0], v0[1]); w.y = cvt_pk_bf16(v0[2], v0[3]); w.z = cvt_pk_bf16(v1[0], v1[1]); w.w = cvt_pk_bf16(v1[2], v1[3]);
;                 *(u32x4*)(XG + (row * DM + cbase + bj * 128)) = w;
;             }
;             ss += __shfl_xor(ss, 16); ss += __shfl_xor(ss, 32);
;             if (fq == 0) red[(128 * ai + 64 * wr + 16 * m + fr) * 4 + wc] = ss;
.LBB0_658:
	s_or_b64 exec, exec, s[4:5]
	v_add_u32_e32 v32, 0x2c000, v188
	s_waitcnt lgkmcnt(0)
	v_mov_b32_e32 v33, v189
	v_lshl_add_u64 v[42:43], v[32:33], 1, s[8:9]
	v_add_u32_e32 v188, 0x2c080, v188
	v_lshl_add_u64 v[40:41], v[188:189], 1, s[8:9]
	s_waitcnt vmcnt(15)
	v_lshlrev_b32_e32 v44, 16, v202
	v_and_b32_e32 v45, 0xffff0000, v202
	v_lshlrev_b32_e32 v46, 16, v203
	v_and_b32_e32 v47, 0xffff0000, v203
	v_lshlrev_b32_e32 v52, 16, v204
	v_and_b32_e32 v53, 0xffff0000, v204
	v_lshlrev_b32_e32 v54, 16, v205
	v_and_b32_e32 v55, 0xffff0000, v205
	v_pk_add_f32 v[30:31], v[30:31], v[46:47]
	v_pk_add_f32 v[28:29], v[28:29], v[44:45]
	v_pk_add_f32 v[44:45], v[26:27], v[54:55]
	v_pk_add_f32 v[26:27], v[24:25], v[52:53]
	v_mul_f32_e32 v24, v29, v29
	v_mul_f32_e32 v25, v31, v31
	v_fmac_f32_e32 v24, v28, v28
	v_fmac_f32_e32 v25, v30, v30
	v_add_f32_e32 v24, v24, v25
	v_mul_f32_e32 v25, v27, v27
	v_mul_f32_e32 v46, v45, v45
	v_fmac_f32_e32 v25, v26, v26
	v_fmac_f32_e32 v46, v44, v44
	v_add_f32_e32 v25, v25, v46
	v_add_f32_e32 v52, v24, v25
	v_cvt_pk_bf16_f32 v24, v28, v29
	v_cvt_pk_bf16_f32 v25, v30, v31
	s_waitcnt vmcnt(14)
	v_lshlrev_b32_e32 v28, 16, v212
	v_and_b32_e32 v29, 0xffff0000, v212
	v_lshlrev_b32_e32 v30, 16, v213
	v_and_b32_e32 v31, 0xffff0000, v213
	v_lshlrev_b32_e32 v46, 16, v214
	v_and_b32_e32 v47, 0xffff0000, v214
	v_pk_add_f32 v[22:23], v[22:23], v[30:31]
	v_pk_add_f32 v[20:21], v[20:21], v[28:29]
	v_lshlrev_b32_e32 v48, 16, v215
	v_and_b32_e32 v49, 0xffff0000, v215
	v_pk_add_f32 v[30:31], v[16:17], v[46:47]
	v_mul_f32_e32 v16, v21, v21
	v_mul_f32_e32 v17, v23, v23
	v_pk_add_f32 v[28:29], v[18:19], v[48:49]
	v_fmac_f32_e32 v16, v20, v20
	v_fmac_f32_e32 v17, v22, v22
	v_add_f32_e32 v16, v16, v17
	v_mul_f32_e32 v17, v31, v31
	v_mul_f32_e32 v18, v29, v29
	v_fmac_f32_e32 v17, v30, v30
	v_fmac_f32_e32 v18, v28, v28
	v_add_f32_e32 v17, v17, v18
	v_add_f32_e32 v16, v16, v17
	v_add_f32_e32 v16, v52, v16
	ds_bpermute_b32 v17, v125, v16
	v_cvt_pk_bf16_f32 v26, v26, v27
	v_cvt_pk_bf16_f32 v27, v44, v45
	global_store_dwordx4 v[58:59], v[24:27], off
	v_cvt_pk_bf16_f32 v18, v20, v21
	s_waitcnt lgkmcnt(0)
	v_add_f32_e32 v16, v16, v17
	ds_bpermute_b32 v17, v126, v16
	v_cvt_pk_bf16_f32 v19, v22, v23
	v_cvt_pk_bf16_f32 v20, v30, v31
	v_cvt_pk_bf16_f32 v21, v28, v29
	global_store_dwordx4 v[56:57], v[18:21], off
	s_and_saveexec_b64 s[4:5], vcc
	s_cbranch_execz .LBB0_660
	s_waitcnt lgkmcnt(0)
	v_add_f32_e32 v16, v16, v17
	ds_write_b32 v124, v16 offset:2560
.LBB0_660:
	s_or_b64 exec, exec, s[4:5]
	s_waitcnt vmcnt(15)
	v_lshlrev_b32_e32 v16, 16, v216
	s_waitcnt lgkmcnt(0)
	v_and_b32_e32 v17, 0xffff0000, v216
	v_lshlrev_b32_e32 v18, 16, v217
	v_and_b32_e32 v19, 0xffff0000, v217
	v_lshlrev_b32_e32 v20, 16, v218
	v_and_b32_e32 v21, 0xffff0000, v218
	v_lshlrev_b32_e32 v22, 16, v219
	v_and_b32_e32 v23, 0xffff0000, v219
	v_pk_add_f32 v[14:15], v[14:15], v[18:19]
	v_pk_add_f32 v[12:13], v[12:13], v[16:17]
	v_pk_add_f32 v[16:17], v[10:11], v[22:23]
	v_pk_add_f32 v[10:11], v[8:9], v[20:21]
	v_mul_f32_e32 v8, v13, v13
	v_mul_f32_e32 v9, v15, v15
	v_fmac_f32_e32 v8, v12, v12
	v_fmac_f32_e32 v9, v14, v14
	v_add_f32_e32 v8, v8, v9
	v_mul_f32_e32 v9, v11, v11
	v_mul_f32_e32 v18, v17, v17
	v_fmac_f32_e32 v9, v10, v10
	v_fmac_f32_e32 v18, v16, v16
	v_add_f32_e32 v9, v9, v18
	v_add_f32_e32 v22, v8, v9
	v_cvt_pk_bf16_f32 v8, v12, v13
	v_cvt_pk_bf16_f32 v9, v14, v15
	s_waitcnt vmcnt(14)
	v_lshlrev_b32_e32 v12, 16, v220
	v_and_b32_e32 v13, 0xffff0000, v220
	v_lshlrev_b32_e32 v14, 16, v221
	v_and_b32_e32 v15, 0xffff0000, v221
	v_lshlrev_b32_e32 v18, 16, v222
	v_and_b32_e32 v19, 0xffff0000, v222
	v_pk_add_f32 v[6:7], v[6:7], v[14:15]
	v_pk_add_f32 v[4:5], v[4:5], v[12:13]
	v_lshlrev_b32_e32 v20, 16, v223
	v_and_b32_e32 v21, 0xffff0000, v223
	v_pk_add_f32 v[14:15], v[0:1], v[18:19]
	v_mul_f32_e32 v0, v5, v5
	v_mul_f32_e32 v1, v7, v7
	v_pk_add_f32 v[12:13], v[2:3], v[20:21]
	v_fmac_f32_e32 v0, v4, v4
	v_fmac_f32_e32 v1, v6, v6
	v_add_f32_e32 v0, v0, v1
	v_mul_f32_e32 v1, v15, v15
	v_mul_f32_e32 v2, v13, v13
	v_fmac_f32_e32 v1, v14, v14
	v_fmac_f32_e32 v2, v12, v12
	v_add_f32_e32 v1, v1, v2
	v_add_f32_e32 v0, v0, v1
	v_add_f32_e32 v0, v22, v0
	ds_bpermute_b32 v1, v125, v0
	v_cvt_pk_bf16_f32 v10, v10, v11
	v_cvt_pk_bf16_f32 v11, v16, v17
	global_store_dwordx4 v[42:43], v[8:11], off
	v_cvt_pk_bf16_f32 v2, v4, v5
	s_waitcnt lgkmcnt(0)
	v_add_f32_e32 v0, v0, v1
	ds_bpermute_b32 v1, v126, v0
	v_cvt_pk_bf16_f32 v3, v6, v7
	v_cvt_pk_bf16_f32 v4, v14, v15
	v_cvt_pk_bf16_f32 v5, v12, v13
	global_store_dwordx4 v[40:41], v[2:5], off
	s_and_saveexec_b64 s[4:5], vcc
	s_cbranch_execz .LBB0_662
	s_waitcnt lgkmcnt(0)
	v_add_f32_e32 v0, v0, v1
	ds_write_b32 v124, v0 offset:2816

; #define PG8_BAR __builtin_amdgcn_s_barrier()
; template <class Epi, class Sched, bool ALIGN_EPI = false, bool SP2 = false>
; __device__ __forceinline__ void gemm_phase(PG8_LAS unsigned char* lds, const int Kdim, const Sched& S, const Epi& E) {
;     ...
;             asm volatile("s_waitcnt lgkmcnt(0)" ::: "memory");
;             PG8_BAR;
;             const unsigned old = *flag;
;             asm volatile("s_waitcnt lgkmcnt(0)" ::: "memory");
;             PG8_BAR;
;             do_epi = (old == 1u);
;             if (do_epi) {
;                 const f32x4* oth = (const f32x4*)(part + ((size_t)cur.tile * 2 + (cur.slice ^ 1)) * 65536) + tid;
; #pragma unroll
;                 for (int a = 0; a < 2; ++a)
; #pragma unroll
;                     for (int b = 0; b < 2; ++b) {
; #pragma unroll
;                         for (int m = 0; m < 4; ++m)
; #pragma unroll
;                             for (int n = 0; n < 2; ++n) acc[a][b][m][n] += oth[(((a * 2 + b) * 4 + m) * 2 + n) * 512];
;                         __builtin_amdgcn_sched_barrier(0);
;                     }
.LBB0_989:
	s_or_b64 exec, exec, s[28:29]
	v_mov_b32_e32 v128, s67
	s_waitcnt lgkmcnt(0)
	s_barrier
	ds_read_b32 v128, v128
	s_waitcnt lgkmcnt(0)
	s_mov_b64 s[26:27], 0
	s_barrier
	s_waitcnt lgkmcnt(0)
	v_cmp_ne_u32_e32 vcc, 1, v128
	s_cbranch_vccnz .LBB0_991
	s_xor_b32 s6, s6, 1
	s_ashr_i32 s7, s6, 31
	s_lshl_b64 s[6:7], s[6:7], 18
	s_add_u32 s0, s0, s6
	s_addc_u32 s1, s1, s7
	v_lshl_add_u64 v[128:129], v[136:137], 4, s[0:1]
	s_mov_b32 s99, 0
	global_load_dwordx4 v[166:169], v[128:129], off
	s_mov_b32 s98, 0x2000
	v_lshl_add_u64 v[186:187], v[128:129], 0, s[98:99]
	global_load_dwordx4 v[170:173], v[186:187], off
	s_mov_b32 s98, 0x4000
	v_lshl_add_u64 v[186:187], v[128:129], 0, s[98:99]
	global_load_dwordx4 v[174:177], v[186:187], off
	s_mov_b32 s98, 0x6000
	v_lshl_add_u64 v[186:187], v[128:129], 0, s[98:99]
	global_load_dwordx4 v[178:181], v[186:187], off
	s_mov_b32 s98, 0x8000
	v_lshl_add_u64 v[186:187], v[128:129], 0, s[98:99]
	global_load_dwordx4 v[182:185], v[186:187], off
	s_mov_b32 s98, 0xa000
	v_lshl_add_u64 v[186:187], v[128:129], 0, s[98:99]
	global_load_dwordx4 v[194:197], v[186:187], off
	s_mov_b32 s98, 0xc000
	v_lshl_add_u64 v[186:187], v[128:129], 0, s[98:99]
	global_load_dwordx4 v[198:201], v[186:187], off
	s_mov_b32 s98, 0xe000
	v_lshl_add_u64 v[186:187], v[128:129], 0, s[98:99]
	global_load_dwordx4 v[202:205], v[186:187], off
	s_mov_b32 s98, 0x10000
	v_lshl_add_u64 v[186:187], v[128:129], 0, s[98:99]
	global_load_dwordx4 v[212:215], v[186:187], off
	s_mov_b32 s98, 0x12000
	v_lshl_add_u64 v[186:187], v[128:129], 0, s[98:99]
	global_load_dwordx4 v[216:219], v[186:187], off
	s_mov_b32 s98, 0x14000
	v_lshl_add_u64 v[186:187], v[128:129], 0, s[98:99]
	global_load_dwordx4 v[220:223], v[186:187], off
	s_mov_b32 s98, 0x16000
	v_lshl_add_u64 v[186:187], v[128:129], 0, s[98:99]
	global_load_dwordx4 v[224:227], v[186:187], off
	s_waitcnt vmcnt(11)
	v_pk_add_f32 v[124:125], v[124:125], v[166:167]
	v_pk_add_f32 v[126:127], v[126:127], v[168:169]
	s_waitcnt vmcnt(10)
	v_pk_add_f32 v[120:121], v[120:121], v[170:171]
	v_pk_add_f32 v[122:123], v[122:123], v[172:173]
	s_waitcnt vmcnt(9)
	v_pk_add_f32 v[108:109], v[108:109], v[174:175]
	v_pk_add_f32 v[110:111], v[110:111], v[176:177]
	s_waitcnt vmcnt(8)
	v_pk_add_f32 v[104:105], v[104:105], v[178:179]
	v_pk_add_f32 v[106:107], v[106:107], v[180:181]
	s_waitcnt vmcnt(7)
	v_pk_add_f32 v[92:93], v[92:93], v[182:183]
	v_pk_add_f32 v[94:95], v[94:95], v[184:185]
	s_waitcnt vmcnt(6)
	v_pk_add_f32 v[88:89], v[88:89], v[194:195]
	v_pk_add_f32 v[90:91], v[90:91], v[196:197]
	s_waitcnt vmcnt(5)
	v_pk_add_f32 v[76:77], v[76:77], v[198:199]
	v_pk_add_f32 v[78:79], v[78:79], v[200:201]
	s_waitcnt vmcnt(4)
	v_pk_add_f32 v[74:75], v[74:75], v[204:205]
	v_pk_add_f32 v[72:73], v[72:73], v[202:203]
	s_waitcnt vmcnt(3)
	v_pk_add_f32 v[116:117], v[116:117], v[212:213]
	v_pk_add_f32 v[118:119], v[118:119], v[214:215]
	s_waitcnt vmcnt(2)
	v_pk_add_f32 v[112:113], v[112:113], v[216:217]
	v_pk_add_f32 v[114:115], v[114:115], v[218:219]
	s_waitcnt vmcnt(1)
	v_pk_add_f32 v[100:101], v[100:101], v[220:221]
	v_pk_add_f32 v[102:103], v[102:103], v[222:223]
	s_waitcnt vmcnt(0)
	v_pk_add_f32 v[96:97], v[96:97], v[224:225]
	v_pk_add_f32 v[98:99], v[98:99], v[226:227]
	s_mov_b32 s98, 0x18000
	v_lshl_add_u64 v[186:187], v[128:129], 0, s[98:99]
	global_load_dwordx4 v[166:169], v[186:187], off
	s_mov_b32 s98, 0x1a000
	v_lshl_add_u64 v[186:187], v[128:129], 0, s[98:99]
	global_load_dwordx4 v[170:173], v[186:187], off
	s_mov_b32 s98, 0x1c000
	v_lshl_add_u64 v[186:187], v[128:129], 0, s[98:99]
	global_load_dwordx4 v[174:177], v[186:187], off
	s_mov_b32 s98, 0x1e000
	v_lshl_add_u64 v[186:187], v[128:129], 0, s[98:99]
	global_load_dwordx4 v[178:181], v[186:187], off
	s_mov_b32 s98, 0x20000
	v_lshl_add_u64 v[186:187], v[128:129], 0, s[98:99]
	global_load_dwordx4 v[182:185], v[186:187], off
	s_mov_b32 s98, 0x22000
	v_lshl_add_u64 v[186:187], v[128:129], 0, s[98:99]
	global_load_dwordx4 v[194:197], v[186:187], off
	s_mov_b32 s98, 0x24000
	v_lshl_add_u64 v[186:187], v[128:129], 0, s[98:99]
	global_load_dwordx4 v[198:201], v[186:187], off
	s_mov_b32 s98, 0x26000
	v_lshl_add_u64 v[186:187], v[128:129], 0, s[98:99]
	global_load_dwordx4 v[202:205], v[186:187], off
	s_mov_b32 s98, 0x28000
	v_lshl_add_u64 v[186:187], v[128:129], 0, s[98:99]
	global_load_dwordx4 v[212:215], v[186:187], off
	s_mov_b32 s98, 0x2a000
	v_lshl_add_u64 v[186:187], v[128:129], 0, s[98:99]
	global_load_dwordx4 v[216:219], v[186:187], off
	s_mov_b32 s98, 0x2c000
	v_lshl_add_u64 v[186:187], v[128:129], 0, s[98:99]
	global_load_dwordx4 v[220:223], v[186:187], off
	s_mov_b32 s98, 0x2e000
	v_lshl_add_u64 v[186:187], v[128:129], 0, s[98:99]
	global_load_dwordx4 v[224:227], v[186:187], off
	s_waitcnt vmcnt(11)
	v_pk_add_f32 v[84:85], v[84:85], v[166:167]
	v_pk_add_f32 v[86:87], v[86:87], v[168:169]
	s_waitcnt vmcnt(10)
	v_pk_add_f32 v[80:81], v[80:81], v[170:171]
	v_pk_add_f32 v[82:83], v[82:83], v[172:173]
	s_waitcnt vmcnt(9)
	v_pk_add_f32 v[68:69], v[68:69], v[174:175]
	v_pk_add_f32 v[70:71], v[70:71], v[176:177]
	s_waitcnt vmcnt(8)
	v_pk_add_f32 v[66:67], v[66:67], v[180:181]
	v_pk_add_f32 v[64:65], v[64:65], v[178:179]
	s_waitcnt vmcnt(7)
	v_pk_add_f32 v[60:61], v[60:61], v[182:183]
	v_pk_add_f32 v[62:63], v[62:63], v[184:185]
	s_waitcnt vmcnt(6)
	v_pk_add_f32 v[56:57], v[56:57], v[194:195]
	v_pk_add_f32 v[58:59], v[58:59], v[196:197]
	s_waitcnt vmcnt(5)
	v_pk_add_f32 v[44:45], v[44:45], v[198:199]
	v_pk_add_f32 v[46:47], v[46:47], v[200:201]
	s_waitcnt vmcnt(4)
	v_pk_add_f32 v[40:41], v[40:41], v[202:203]
	v_pk_add_f32 v[42:43], v[42:43], v[204:205]
	s_waitcnt vmcnt(3)
; #define LAS __attribute__((address_space(3)))
; template <class Epi, class Sched, bool ALIGN_EPI = false, bool SP2 = false>
; __device__ __forceinline__ void gemm_phase(PG8_LAS unsigned char* lds, const int Kdim, const Sched& S, const Epi& E) {
;     ...
;             if (do_epi) {
;                 const f32x4* oth = (const f32x4*)(part + ((size_t)cur.tile * 2 + (cur.slice ^ 1)) * 65536) + tid;
; #pragma unroll
;                 for (int a = 0; a < 2; ++a)
; #pragma unroll
;                     for (int b = 0; b < 2; ++b) {
; #pragma unroll
;                         for (int m = 0; m < 4; ++m)
; #pragma unroll
;                             for (int n = 0; n < 2; ++n) acc[a][b][m][n] += oth[(((a * 2 + b) * 4 + m) * 2 + n) * 512];
;                         __builtin_amdgcn_sched_barrier(0);
;                     }
;     __device__ __forceinline__ void operator()(f32x4 (&acc)[2][2][4][2], const Unit& u, int ui, int wr, int wc, int fr, int fq, int lane, LAS unsigned char* lds) const {
;     ...
;         const unsigned cbase = (unsigned)(u.pn * 256 + wc * 32 + 8 * fq), rb = (unsigned)(u.pm * 256 + 64 * wr + fr);
;         LAS float* red = (LAS float*)(lds + EXTRA_OFF);
;         u32x4 xin[2][2];
;     ...
;         EPR_LOAD(0, 0);
; #pragma unroll
;         for (int it = 0; it < 8; ++it) {
;             if (it + 1 < 8) EPR_LOAD(it + 1, (it + 1) & 1);
;             __builtin_amdgcn_sched_barrier(0);
;             const int ai = it >> 2, m = it & 3;
;             const unsigned row = rb + 128 * ai + 16 * m;
;             float ss = 0.f;
; #pragma unroll
;             for (int bj = 0; bj < 2; ++bj) {
;                 const u32x4 xw = xin[it & 1][bj];
;                 f32x4 v0, v1;
;                 v0[0] = __builtin_bit_cast(float, xw.x << 16); v0[1] = __builtin_bit_cast(float, xw.x & 0xffff0000u); v0[2] = __builtin_bit_cast(float, xw.y << 16); v0[3] = __builtin_bit_cast(float, xw.y & 0xffff0000u);
;                 v1[0] = __builtin_bit_cast(float, xw.z << 16); v1[1] = __builtin_bit_cast(float, xw.z & 0xffff0000u); v1[2] = __builtin_bit_cast(float, xw.w << 16); v1[3] = __builtin_bit_cast(float, xw.w & 0xffff0000u);
;                 v0 += acc[ai][bj][m][0]; v1 += acc[ai][bj][m][1];
;                 ss += ((v0[0] * v0[0] + v0[1] * v0[1]) + (v0[2] * v0[2] + v0[3] * v0[3])) + ((v1[0] * v1[0] + v1[1] * v1[1]) + (v1[2] * v1[2] + v1[3] * v1[3]));
	v_pk_add_f32 v[28:29], v[28:29], v[212:213]
	v_pk_add_f32 v[30:31], v[30:31], v[214:215]
	s_waitcnt vmcnt(2)
	v_pk_add_f32 v[24:25], v[24:25], v[216:217]
	v_pk_add_f32 v[26:27], v[26:27], v[218:219]
	s_waitcnt vmcnt(1)
	v_pk_add_f32 v[12:13], v[12:13], v[220:221]
	v_pk_add_f32 v[14:15], v[14:15], v[222:223]
	s_waitcnt vmcnt(0)
	v_pk_add_f32 v[10:11], v[10:11], v[226:227]
	v_pk_add_f32 v[8:9], v[8:9], v[224:225]
	s_mov_b32 s98, 0x30000
	v_lshl_add_u64 v[186:187], v[128:129], 0, s[98:99]
	global_load_dwordx4 v[166:169], v[186:187], off
	s_mov_b32 s98, 0x32000
	v_lshl_add_u64 v[186:187], v[128:129], 0, s[98:99]
	global_load_dwordx4 v[170:173], v[186:187], off
	s_mov_b32 s98, 0x34000
	v_lshl_add_u64 v[186:187], v[128:129], 0, s[98:99]
	global_load_dwordx4 v[174:177], v[186:187], off
	s_mov_b32 s98, 0x36000
	v_lshl_add_u64 v[186:187], v[128:129], 0, s[98:99]
	global_load_dwordx4 v[178:181], v[186:187], off
	s_mov_b32 s98, 0x38000
	v_lshl_add_u64 v[186:187], v[128:129], 0, s[98:99]
	global_load_dwordx4 v[182:185], v[186:187], off
	s_mov_b32 s98, 0x3a000
	v_lshl_add_u64 v[186:187], v[128:129], 0, s[98:99]
	global_load_dwordx4 v[194:197], v[186:187], off
	s_mov_b32 s98, 0x3c000
	v_lshl_add_u64 v[186:187], v[128:129], 0, s[98:99]
	global_load_dwordx4 v[198:201], v[186:187], off
	s_mov_b32 s98, 0x3e000
	v_lshl_add_u64 v[186:187], v[128:129], 0, s[98:99]
	global_load_dwordx4 v[202:205], v[186:187], off
	s_waitcnt vmcnt(7)
	v_pk_add_f32 v[52:53], v[52:53], v[166:167]
	v_pk_add_f32 v[54:55], v[54:55], v[168:169]
	s_waitcnt vmcnt(6)
	v_pk_add_f32 v[48:49], v[48:49], v[170:171]
	v_pk_add_f32 v[50:51], v[50:51], v[172:173]
	s_waitcnt vmcnt(5)
	v_pk_add_f32 v[36:37], v[36:37], v[174:175]
	v_pk_add_f32 v[38:39], v[38:39], v[176:177]
	s_waitcnt vmcnt(4)
	v_pk_add_f32 v[32:33], v[32:33], v[178:179]
	v_pk_add_f32 v[34:35], v[34:35], v[180:181]
	s_waitcnt vmcnt(3)
	v_pk_add_f32 v[20:21], v[20:21], v[182:183]
	v_pk_add_f32 v[22:23], v[22:23], v[184:185]
	s_waitcnt vmcnt(2)
	v_pk_add_f32 v[16:17], v[16:17], v[194:195]
	v_pk_add_f32 v[18:19], v[18:19], v[196:197]
	s_waitcnt vmcnt(1)
	v_pk_add_f32 v[4:5], v[4:5], v[198:199]
	v_pk_add_f32 v[6:7], v[6:7], v[200:201]
	s_waitcnt vmcnt(0)
	v_pk_add_f32 v[2:3], v[2:3], v[204:205]
	v_pk_add_f32 v[0:1], v[0:1], v[202:203]
	s_mov_b64 s[26:27], -1
.LBB0_991:
	s_and_b64 vcc, exec, s[26:27]
	s_cbranch_vccz .LBB0_1011
	v_mov_b32_e32 v128, v145
	v_mov_b32_e32 v148, v146
	v_mov_b32_e32 v130, v147
	s_lshl_b32 s0, s43, 8
	s_lshl_b32 s1, s44, 18
	v_add_u32_e32 v149, s55, v128
	s_or_b32 s0, s0, s57
	v_lshlrev_b32_e32 v129, 3, v130
	v_lshlrev_b32_e32 v128, 10, v149
	s_add_i32 s0, s0, s1
	v_add3_u32 v138, s0, v129, v128
	v_add_u32_e32 v128, 0x80, v138
	v_mov_b32_e32 v129, v189
	v_lshl_add_u64 v[160:161], v[128:129], 1, s[10:11]
	v_add_u32_e32 v128, 0x4000, v138
	v_lshl_add_u64 v[140:141], v[128:129], 1, s[10:11]
	v_add_u32_e32 v128, 0x4080, v138
	v_mov_b32_e32 v139, v189
	v_lshl_add_u64 v[142:143], v[128:129], 1, s[10:11]
	v_lshl_add_u64 v[158:159], v[138:139], 1, s[10:11]
	v_cmp_eq_u32_e32 vcc, 0, v130
	global_load_dwordx4 v[132:135], v[140:141], off
	global_load_dwordx4 v[128:131], v[142:143], off
	global_load_dwordx4 v[150:153], v[158:159], off
	global_load_dwordx4 v[154:157], v[160:161], off
	s_mov_b32 s99, 0
	s_mov_b32 s98, 0x10000
	v_lshl_add_u64 v[186:187], v[158:159], 0, s[98:99]
	global_load_dwordx4 v[166:169], v[186:187], off
	global_load_dwordx4 v[170:173], v[186:187], off offset:256
	s_mov_b32 s98, 0x18000
	v_lshl_add_u64 v[186:187], v[158:159], 0, s[98:99]
	global_load_dwordx4 v[174:177], v[186:187], off
	global_load_dwordx4 v[178:181], v[186:187], off offset:256
	s_mov_b32 s98, 0x40000
	v_lshl_add_u64 v[186:187], v[158:159], 0, s[98:99]
	global_load_dwordx4 v[182:185], v[186:187], off
	global_load_dwordx4 v[194:197], v[186:187], off offset:256
	s_mov_b32 s98, 0x48000
	v_lshl_add_u64 v[186:187], v[158:159], 0, s[98:99]
	global_load_dwordx4 v[198:201], v[186:187], off
	global_load_dwordx4 v[202:205], v[186:187], off offset:256
	s_mov_b32 s98, 0x50000
	v_lshl_add_u64 v[186:187], v[158:159], 0, s[98:99]
	global_load_dwordx4 v[212:215], v[186:187], off
	global_load_dwordx4 v[216:219], v[186:187], off offset:256
	s_mov_b32 s98, 0x58000
	v_lshl_add_u64 v[186:187], v[158:159], 0, s[98:99]
	global_load_dwordx4 v[220:223], v[186:187], off
	global_load_dwordx4 v[224:227], v[186:187], off offset:256
	s_waitcnt vmcnt(12)
	v_lshlrev_b32_e32 v162, 16, v150
	v_and_b32_e32 v163, 0xffff0000, v150
	v_lshlrev_b32_e32 v150, 16, v151
	v_and_b32_e32 v151, 0xffff0000, v151
	v_lshlrev_b32_e32 v164, 16, v152
	v_and_b32_e32 v165, 0xffff0000, v152
	v_lshlrev_b32_e32 v152, 16, v153
	v_and_b32_e32 v153, 0xffff0000, v153
	v_pk_add_f32 v[126:127], v[126:127], v[150:151]
	v_pk_add_f32 v[124:125], v[124:125], v[162:163]
	v_pk_add_f32 v[150:151], v[122:123], v[152:153]
	v_pk_add_f32 v[122:123], v[120:121], v[164:165]
	v_mul_f32_e32 v120, v125, v125
	v_mul_f32_e32 v121, v127, v127
	v_fmac_f32_e32 v120, v124, v124
	v_fmac_f32_e32 v121, v126, v126
	v_add_f32_e32 v120, v120, v121
	v_mul_f32_e32 v121, v123, v123
	v_mul_f32_e32 v139, v151, v151
	v_fmac_f32_e32 v121, v122, v122
	v_fmac_f32_e32 v139, v150, v150
	v_add_f32_e32 v121, v121, v139
	v_add_f32_e32 v139, v120, v121
	v_cvt_pk_bf16_f32 v120, v124, v125
	v_cvt_pk_bf16_f32 v121, v126, v127
	v_lshlrev_b32_e32 v124, 16, v154
	v_and_b32_e32 v125, 0xffff0000, v154
	v_lshlrev_b32_e32 v126, 16, v155
	v_and_b32_e32 v127, 0xffff0000, v155
	v_lshlrev_b32_e32 v152, 16, v156
	v_and_b32_e32 v153, 0xffff0000, v156
	v_pk_add_f32 v[118:119], v[118:119], v[126:127]
	v_pk_add_f32 v[116:117], v[116:117], v[124:125]
	v_lshlrev_b32_e32 v154, 16, v157
	v_and_b32_e32 v155, 0xffff0000, v157
	v_pk_add_f32 v[152:153], v[112:113], v[152:153]
	v_mul_f32_e32 v112, v117, v117
	v_mul_f32_e32 v113, v119, v119
	v_pk_add_f32 v[154:155], v[114:115], v[154:155]
	v_fmac_f32_e32 v112, v116, v116
	v_fmac_f32_e32 v113, v118, v118
	v_add_f32_e32 v112, v112, v113
	v_mul_f32_e32 v113, v153, v153
	v_mul_f32_e32 v114, v155, v155
	v_fmac_f32_e32 v113, v152, v152
	v_fmac_f32_e32 v114, v154, v154
	v_add_f32_e32 v113, v113, v114
	v_and_b32_e32 v114, 64, v208
	v_add_f32_e32 v112, v112, v113
	v_xor_b32_e32 v113, 16, v208
	v_add_u32_e32 v124, 64, v114
	v_cmp_lt_i32_e64 s[6:7], v113, v124
	v_add_f32_e32 v112, v139, v112
	v_cvt_pk_bf16_f32 v122, v122, v123
	v_cvt_pk_bf16_f32 v123, v150, v151
	global_store_dwordx4 v[158:159], v[120:123], off
	v_cndmask_b32_e64 v113, v208, v113, s[6:7]
	v_lshlrev_b32_e32 v125, 2, v113
	ds_bpermute_b32 v113, v125, v112
	v_cvt_pk_bf16_f32 v114, v116, v117
	v_cvt_pk_bf16_f32 v115, v118, v119
	v_cvt_pk_bf16_f32 v116, v152, v153
	v_cvt_pk_bf16_f32 v117, v154, v155
	s_waitcnt lgkmcnt(0)
; __device__ __forceinline__ unsigned cvt_pk_bf16(float lo, float hi) { unsigned r; asm volatile("v_cvt_pk_bf16_f32 %0, %1, %2" : "=v"(r) : "v"(lo), "v"(hi)); return r; }
; #define EPR_LOAD(IT, BUF) do { const unsigned row_ = rb + 128 * ((IT) >> 2) + 16 * ((IT) & 3); _Pragma("unroll") for (int bj = 0; bj < 2; ++bj) \
;             xin[BUF][bj] = *(const u32x4*)(XG + (row_ * DM + cbase + bj * 128)); } while (0)
;     __device__ __forceinline__ void operator()(f32x4 (&acc)[2][2][4][2], const Unit& u, int ui, int wr, int wc, int fr, int fq, int lane, LAS unsigned char* lds) const {
;     ...
;         for (int it = 0; it < 8; ++it) {
;             if (it + 1 < 8) EPR_LOAD(it + 1, (it + 1) & 1);
;             __builtin_amdgcn_sched_barrier(0);
;             const int ai = it >> 2, m = it & 3;
;             const unsigned row = rb + 128 * ai + 16 * m;
;             float ss = 0.f;
; #pragma unroll
;             for (int bj = 0; bj < 2; ++bj) {
;                 const u32x4 xw = xin[it & 1][bj];
;                 f32x4 v0, v1;
;                 v0[0] = __builtin_bit_cast(float, xw.x << 16); v0[1] = __builtin_bit_cast(float, xw.x & 0xffff0000u); v0[2] = __builtin_bit_cast(float, xw.y << 16); v0[3] = __builtin_bit_cast(float, xw.y & 0xffff0000u);
;                 v1[0] = __builtin_bit_cast(float, xw.z << 16); v1[1] = __builtin_bit_cast(float, xw.z & 0xffff0000u); v1[2] = __builtin_bit_cast(float, xw.w << 16); v1[3] = __builtin_bit_cast(float, xw.w & 0xffff0000u);
;                 v0 += acc[ai][bj][m][0]; v1 += acc[ai][bj][m][1];
;                 ss += ((v0[0] * v0[0] + v0[1] * v0[1]) + (v0[2] * v0[2] + v0[3] * v0[3])) + ((v1[0] * v1[0] + v1[1] * v1[1]) + (v1[2] * v1[2] + v1[3] * v1[3]));
;                 u32x4 w; w.x = cvt_pk_bf16(v0[0], v0[1]); w.y = cvt_pk_bf16(v0[2], v0[3]); w.z = cvt_pk_bf16(v1[0], v1[1]); w.w = cvt_pk_bf16(v1[2], v1[3]);
;                 *(u32x4*)(XG + (row * DM + cbase + bj * 128)) = w;
;             }
;             ss += __shfl_xor(ss, 16); ss += __shfl_xor(ss, 32);
;             if (fq == 0) red[(128 * ai + 64 * wr + 16 * m + fr) * 4 + wc] = ss;
	v_add_f32_e32 v112, v112, v113
	v_xor_b32_e32 v113, 32, v208
	v_cmp_lt_i32_e64 s[6:7], v113, v124
	v_lshl_add_u32 v124, v149, 4, s70
	global_store_dwordx4 v[160:161], v[114:117], off
	v_cndmask_b32_e64 v113, v208, v113, s[6:7]
	v_lshlrev_b32_e32 v126, 2, v113
	ds_bpermute_b32 v113, v126, v112
	s_and_saveexec_b64 s[6:7], vcc
	s_cbranch_execz .LBB0_994
	s_waitcnt lgkmcnt(0)
	v_add_f32_e32 v112, v112, v113
	ds_write_b32 v124, v112
.LBB0_994:
	s_or_b64 exec, exec, s[6:7]
	v_add_u32_e32 v112, 0x8000, v138
	s_waitcnt lgkmcnt(0)
	v_mov_b32_e32 v113, v189
	v_lshl_add_u64 v[122:123], v[112:113], 1, s[10:11]
	v_add_u32_e32 v112, 0x8080, v138
	v_lshl_add_u64 v[120:121], v[112:113], 1, s[10:11]
	v_lshlrev_b32_e32 v150, 16, v132
	v_and_b32_e32 v151, 0xffff0000, v132
	v_lshlrev_b32_e32 v132, 16, v133
	v_and_b32_e32 v133, 0xffff0000, v133
	v_lshlrev_b32_e32 v152, 16, v134
	v_and_b32_e32 v153, 0xffff0000, v134
	v_lshlrev_b32_e32 v134, 16, v135
	v_and_b32_e32 v135, 0xffff0000, v135
	v_pk_add_f32 v[110:111], v[110:111], v[132:133]
	v_pk_add_f32 v[108:109], v[108:109], v[150:151]
	v_pk_add_f32 v[132:133], v[106:107], v[134:135]
	v_pk_add_f32 v[106:107], v[104:105], v[152:153]
	v_mul_f32_e32 v104, v109, v109
	v_mul_f32_e32 v105, v111, v111
	v_fmac_f32_e32 v104, v108, v108
	v_fmac_f32_e32 v105, v110, v110
	v_add_f32_e32 v104, v104, v105
	v_mul_f32_e32 v105, v107, v107
	v_mul_f32_e32 v127, v133, v133
	v_fmac_f32_e32 v105, v106, v106
	v_fmac_f32_e32 v127, v132, v132
	v_add_f32_e32 v105, v105, v127
	v_add_f32_e32 v127, v104, v105
	v_cvt_pk_bf16_f32 v104, v108, v109
	v_cvt_pk_bf16_f32 v105, v110, v111
	v_lshlrev_b32_e32 v108, 16, v128
	v_and_b32_e32 v109, 0xffff0000, v128
	v_lshlrev_b32_e32 v110, 16, v129
	v_and_b32_e32 v111, 0xffff0000, v129
	v_lshlrev_b32_e32 v128, 16, v130
	v_and_b32_e32 v129, 0xffff0000, v130
	v_pk_add_f32 v[102:103], v[102:103], v[110:111]
	v_pk_add_f32 v[100:101], v[100:101], v[108:109]
	v_lshlrev_b32_e32 v130, 16, v131
	v_and_b32_e32 v131, 0xffff0000, v131
	v_pk_add_f32 v[110:111], v[96:97], v[128:129]
	v_mul_f32_e32 v96, v101, v101
	v_mul_f32_e32 v97, v103, v103
	v_pk_add_f32 v[108:109], v[98:99], v[130:131]
	v_fmac_f32_e32 v96, v100, v100
	v_fmac_f32_e32 v97, v102, v102
	v_add_f32_e32 v96, v96, v97
	v_mul_f32_e32 v97, v111, v111
	v_mul_f32_e32 v98, v109, v109
	v_fmac_f32_e32 v97, v110, v110
	v_fmac_f32_e32 v98, v108, v108
	v_add_f32_e32 v97, v97, v98
	v_add_f32_e32 v96, v96, v97
	v_add_f32_e32 v96, v127, v96
	ds_bpermute_b32 v97, v125, v96
	v_cvt_pk_bf16_f32 v106, v106, v107
	v_cvt_pk_bf16_f32 v107, v132, v133
	global_store_dwordx4 v[140:141], v[104:107], off
	v_cvt_pk_bf16_f32 v98, v100, v101
	s_waitcnt lgkmcnt(0)
	v_add_f32_e32 v96, v96, v97
	ds_bpermute_b32 v97, v126, v96
	v_cvt_pk_bf16_f32 v99, v102, v103
	v_cvt_pk_bf16_f32 v100, v110, v111
	v_cvt_pk_bf16_f32 v101, v108, v109
	global_store_dwordx4 v[142:143], v[98:101], off
	s_and_saveexec_b64 s[6:7], vcc
	s_cbranch_execz .LBB0_996
	s_waitcnt lgkmcnt(0)
	v_add_f32_e32 v96, v96, v97
	ds_write_b32 v124, v96 offset:256
.LBB0_996:
	s_or_b64 exec, exec, s[6:7]
	v_add_u32_e32 v96, 0xc000, v138
	s_waitcnt lgkmcnt(0)
	v_mov_b32_e32 v97, v189
	v_lshl_add_u64 v[106:107], v[96:97], 1, s[10:11]
	v_add_u32_e32 v96, 0xc080, v138
	v_lshl_add_u64 v[104:105], v[96:97], 1, s[10:11]
	s_waitcnt vmcnt(15)
	v_lshlrev_b32_e32 v108, 16, v166
	v_and_b32_e32 v109, 0xffff0000, v166
	v_lshlrev_b32_e32 v110, 16, v167
	v_and_b32_e32 v111, 0xffff0000, v167
	v_lshlrev_b32_e32 v116, 16, v168
	v_and_b32_e32 v117, 0xffff0000, v168
	v_lshlrev_b32_e32 v118, 16, v169
	v_and_b32_e32 v119, 0xffff0000, v169
	v_pk_add_f32 v[94:95], v[94:95], v[110:111]
	v_pk_add_f32 v[92:93], v[92:93], v[108:109]
	v_pk_add_f32 v[108:109], v[90:91], v[118:119]
	v_pk_add_f32 v[90:91], v[88:89], v[116:117]
	v_mul_f32_e32 v88, v93, v93
	v_mul_f32_e32 v89, v95, v95
	v_fmac_f32_e32 v88, v92, v92
	v_fmac_f32_e32 v89, v94, v94
	v_add_f32_e32 v88, v88, v89
	v_mul_f32_e32 v89, v91, v91
	v_mul_f32_e32 v110, v109, v109
	v_fmac_f32_e32 v89, v90, v90
	v_fmac_f32_e32 v110, v108, v108
	v_add_f32_e32 v89, v89, v110
	v_add_f32_e32 v116, v88, v89
	v_cvt_pk_bf16_f32 v88, v92, v93
	v_cvt_pk_bf16_f32 v89, v94, v95
	s_waitcnt vmcnt(14)
	v_lshlrev_b32_e32 v92, 16, v170
	v_and_b32_e32 v93, 0xffff0000, v170
	v_lshlrev_b32_e32 v94, 16, v171
	v_and_b32_e32 v95, 0xffff0000, v171
	v_lshlrev_b32_e32 v110, 16, v172
	v_and_b32_e32 v111, 0xffff0000, v172
	v_pk_add_f32 v[86:87], v[86:87], v[94:95]
	v_pk_add_f32 v[84:85], v[84:85], v[92:93]
	v_lshlrev_b32_e32 v112, 16, v173
	v_and_b32_e32 v113, 0xffff0000, v173
	v_pk_add_f32 v[94:95], v[80:81], v[110:111]
	v_mul_f32_e32 v80, v85, v85
	v_mul_f32_e32 v81, v87, v87
	v_pk_add_f32 v[92:93], v[82:83], v[112:113]
	v_fmac_f32_e32 v80, v84, v84
	v_fmac_f32_e32 v81, v86, v86
	v_add_f32_e32 v80, v80, v81
	v_mul_f32_e32 v81, v95, v95
	v_mul_f32_e32 v82, v93, v93
	v_fmac_f32_e32 v81, v94, v94
	v_fmac_f32_e32 v82, v92, v92
	v_add_f32_e32 v81, v81, v82
	v_add_f32_e32 v80, v80, v81
	v_add_f32_e32 v80, v116, v80
	ds_bpermute_b32 v81, v125, v80
	v_cvt_pk_bf16_f32 v90, v90, v91
	v_cvt_pk_bf16_f32 v91, v108, v109
	global_store_dwordx4 v[122:123], v[88:91], off
	v_cvt_pk_bf16_f32 v82, v84, v85
	s_waitcnt lgkmcnt(0)
	v_add_f32_e32 v80, v80, v81
	ds_bpermute_b32 v81, v126, v80
	v_cvt_pk_bf16_f32 v83, v86, v87
	v_cvt_pk_bf16_f32 v84, v94, v95
	v_cvt_pk_bf16_f32 v85, v92, v93
	global_store_dwordx4 v[120:121], v[82:85], off
	s_and_saveexec_b64 s[6:7], vcc
	s_cbranch_execz .LBB0_998
	s_waitcnt lgkmcnt(0)
	v_add_f32_e32 v80, v80, v81
	ds_write_b32 v124, v80 offset:512
; __device__ __forceinline__ unsigned cvt_pk_bf16(float lo, float hi) { unsigned r; asm volatile("v_cvt_pk_bf16_f32 %0, %1, %2" : "=v"(r) : "v"(lo), "v"(hi)); return r; }
; #define EPR_LOAD(IT, BUF) do { const unsigned row_ = rb + 128 * ((IT) >> 2) + 16 * ((IT) & 3); _Pragma("unroll") for (int bj = 0; bj < 2; ++bj) \
;             xin[BUF][bj] = *(const u32x4*)(XG + (row_ * DM + cbase + bj * 128)); } while (0)
;     __device__ __forceinline__ void operator()(f32x4 (&acc)[2][2][4][2], const Unit& u, int ui, int wr, int wc, int fr, int fq, int lane, LAS unsigned char* lds) const {
;     ...
;         for (int it = 0; it < 8; ++it) {
;             if (it + 1 < 8) EPR_LOAD(it + 1, (it + 1) & 1);
;             __builtin_amdgcn_sched_barrier(0);
;             const int ai = it >> 2, m = it & 3;
;             const unsigned row = rb + 128 * ai + 16 * m;
;             float ss = 0.f;
; #pragma unroll
;             for (int bj = 0; bj < 2; ++bj) {
;                 const u32x4 xw = xin[it & 1][bj];
;                 f32x4 v0, v1;
;                 v0[0] = __builtin_bit_cast(float, xw.x << 16); v0[1] = __builtin_bit_cast(float, xw.x & 0xffff0000u); v0[2] = __builtin_bit_cast(float, xw.y << 16); v0[3] = __builtin_bit_cast(float, xw.y & 0xffff0000u);
;                 v1[0] = __builtin_bit_cast(float, xw.z << 16); v1[1] = __builtin_bit_cast(float, xw.z & 0xffff0000u); v1[2] = __builtin_bit_cast(float, xw.w << 16); v1[3] = __builtin_bit_cast(float, xw.w & 0xffff0000u);
;                 v0 += acc[ai][bj][m][0]; v1 += acc[ai][bj][m][1];
;                 ss += ((v0[0] * v0[0] + v0[1] * v0[1]) + (v0[2] * v0[2] + v0[3] * v0[3])) + ((v1[0] * v1[0] + v1[1] * v1[1]) + (v1[2] * v1[2] + v1[3] * v1[3]));
;                 u32x4 w; w.x = cvt_pk_bf16(v0[0], v0[1]); w.y = cvt_pk_bf16(v0[2], v0[3]); w.z = cvt_pk_bf16(v1[0], v1[1]); w.w = cvt_pk_bf16(v1[2], v1[3]);
;                 *(u32x4*)(XG + (row * DM + cbase + bj * 128)) = w;
;             }
;             ss += __shfl_xor(ss, 16); ss += __shfl_xor(ss, 32);
;             if (fq == 0) red[(128 * ai + 64 * wr + 16 * m + fr) * 4 + wc] = ss;
.LBB0_998:
	s_or_b64 exec, exec, s[6:7]
	v_add_u32_e32 v80, 0x20000, v138
	s_waitcnt lgkmcnt(0)
	v_mov_b32_e32 v81, v189
	v_lshl_add_u64 v[90:91], v[80:81], 1, s[10:11]
	v_add_u32_e32 v80, 0x20080, v138
	v_lshl_add_u64 v[88:89], v[80:81], 1, s[10:11]
	s_waitcnt vmcnt(15)
	v_lshlrev_b32_e32 v92, 16, v174
	v_and_b32_e32 v93, 0xffff0000, v174
	v_lshlrev_b32_e32 v94, 16, v175
	v_and_b32_e32 v95, 0xffff0000, v175
	v_lshlrev_b32_e32 v100, 16, v176
	v_and_b32_e32 v101, 0xffff0000, v176
	v_lshlrev_b32_e32 v102, 16, v177
	v_and_b32_e32 v103, 0xffff0000, v177
	v_pk_add_f32 v[78:79], v[78:79], v[94:95]
	v_pk_add_f32 v[76:77], v[76:77], v[92:93]
	v_pk_add_f32 v[92:93], v[74:75], v[102:103]
	v_pk_add_f32 v[74:75], v[72:73], v[100:101]
	v_mul_f32_e32 v72, v77, v77
	v_mul_f32_e32 v73, v79, v79
	v_fmac_f32_e32 v72, v76, v76
	v_fmac_f32_e32 v73, v78, v78
	v_add_f32_e32 v72, v72, v73
	v_mul_f32_e32 v73, v75, v75
	v_mul_f32_e32 v94, v93, v93
	v_fmac_f32_e32 v73, v74, v74
	v_fmac_f32_e32 v94, v92, v92
	v_add_f32_e32 v73, v73, v94
	v_add_f32_e32 v100, v72, v73
	v_cvt_pk_bf16_f32 v72, v76, v77
	v_cvt_pk_bf16_f32 v73, v78, v79
	s_waitcnt vmcnt(14)
	v_lshlrev_b32_e32 v76, 16, v178
	v_and_b32_e32 v77, 0xffff0000, v178
	v_lshlrev_b32_e32 v78, 16, v179
	v_and_b32_e32 v79, 0xffff0000, v179
	v_lshlrev_b32_e32 v94, 16, v180
	v_and_b32_e32 v95, 0xffff0000, v180
	v_pk_add_f32 v[70:71], v[70:71], v[78:79]
	v_pk_add_f32 v[68:69], v[68:69], v[76:77]
	v_lshlrev_b32_e32 v96, 16, v181
	v_and_b32_e32 v97, 0xffff0000, v181
	v_pk_add_f32 v[78:79], v[64:65], v[94:95]
	v_mul_f32_e32 v64, v69, v69
	v_mul_f32_e32 v65, v71, v71
	v_pk_add_f32 v[76:77], v[66:67], v[96:97]
	v_fmac_f32_e32 v64, v68, v68
	v_fmac_f32_e32 v65, v70, v70
	v_add_f32_e32 v64, v64, v65
	v_mul_f32_e32 v65, v79, v79
	v_mul_f32_e32 v66, v77, v77
	v_fmac_f32_e32 v65, v78, v78
	v_fmac_f32_e32 v66, v76, v76
	v_add_f32_e32 v65, v65, v66
	v_add_f32_e32 v64, v64, v65
	v_add_f32_e32 v64, v100, v64
	ds_bpermute_b32 v65, v125, v64
	v_cvt_pk_bf16_f32 v74, v74, v75
	v_cvt_pk_bf16_f32 v75, v92, v93
	global_store_dwordx4 v[106:107], v[72:75], off
	v_cvt_pk_bf16_f32 v66, v68, v69
	s_waitcnt lgkmcnt(0)
	v_add_f32_e32 v64, v64, v65
	ds_bpermute_b32 v65, v126, v64
	v_cvt_pk_bf16_f32 v67, v70, v71
	v_cvt_pk_bf16_f32 v68, v78, v79
	v_cvt_pk_bf16_f32 v69, v76, v77
	global_store_dwordx4 v[104:105], v[66:69], off
	s_and_saveexec_b64 s[6:7], vcc
	s_cbranch_execz .LBB0_1000
	s_waitcnt lgkmcnt(0)
	v_add_f32_e32 v64, v64, v65
	ds_write_b32 v124, v64 offset:768
.LBB0_1000:
	s_or_b64 exec, exec, s[6:7]
	v_add_u32_e32 v64, 0x24000, v138
	s_waitcnt lgkmcnt(0)
	v_mov_b32_e32 v65, v189
	v_lshl_add_u64 v[74:75], v[64:65], 1, s[10:11]
	v_add_u32_e32 v64, 0x24080, v138
	v_lshl_add_u64 v[72:73], v[64:65], 1, s[10:11]
	s_waitcnt vmcnt(15)
	v_lshlrev_b32_e32 v76, 16, v182
	v_and_b32_e32 v77, 0xffff0000, v182
	v_lshlrev_b32_e32 v78, 16, v183
	v_and_b32_e32 v79, 0xffff0000, v183
	v_lshlrev_b32_e32 v84, 16, v184
	v_and_b32_e32 v85, 0xffff0000, v184
	v_lshlrev_b32_e32 v86, 16, v185
	v_and_b32_e32 v87, 0xffff0000, v185
	v_pk_add_f32 v[62:63], v[62:63], v[78:79]
	v_pk_add_f32 v[60:61], v[60:61], v[76:77]
	v_pk_add_f32 v[76:77], v[58:59], v[86:87]
	v_pk_add_f32 v[58:59], v[56:57], v[84:85]
	v_mul_f32_e32 v56, v61, v61
	v_mul_f32_e32 v57, v63, v63
	v_fmac_f32_e32 v56, v60, v60
	v_fmac_f32_e32 v57, v62, v62
	v_add_f32_e32 v56, v56, v57
	v_mul_f32_e32 v57, v59, v59
	v_mul_f32_e32 v78, v77, v77
	v_fmac_f32_e32 v57, v58, v58
	v_fmac_f32_e32 v78, v76, v76
	v_add_f32_e32 v57, v57, v78
	v_add_f32_e32 v84, v56, v57
	v_cvt_pk_bf16_f32 v56, v60, v61
	v_cvt_pk_bf16_f32 v57, v62, v63
	s_waitcnt vmcnt(14)
	v_lshlrev_b32_e32 v60, 16, v194
	v_and_b32_e32 v61, 0xffff0000, v194
	v_lshlrev_b32_e32 v62, 16, v195
	v_and_b32_e32 v63, 0xffff0000, v195
	v_lshlrev_b32_e32 v78, 16, v196
	v_and_b32_e32 v79, 0xffff0000, v196
	v_pk_add_f32 v[54:55], v[54:55], v[62:63]
	v_pk_add_f32 v[52:53], v[52:53], v[60:61]
	v_lshlrev_b32_e32 v80, 16, v197
	v_and_b32_e32 v81, 0xffff0000, v197
	v_pk_add_f32 v[62:63], v[48:49], v[78:79]
	v_mul_f32_e32 v48, v53, v53
	v_mul_f32_e32 v49, v55, v55
	v_pk_add_f32 v[60:61], v[50:51], v[80:81]
	v_fmac_f32_e32 v48, v52, v52
	v_fmac_f32_e32 v49, v54, v54
	v_add_f32_e32 v48, v48, v49
	v_mul_f32_e32 v49, v63, v63
	v_mul_f32_e32 v50, v61, v61
	v_fmac_f32_e32 v49, v62, v62
	v_fmac_f32_e32 v50, v60, v60
	v_add_f32_e32 v49, v49, v50
	v_add_f32_e32 v48, v48, v49
	v_add_f32_e32 v48, v84, v48
	ds_bpermute_b32 v49, v125, v48
	v_cvt_pk_bf16_f32 v58, v58, v59
	v_cvt_pk_bf16_f32 v59, v76, v77
	global_store_dwordx4 v[90:91], v[56:59], off
	v_cvt_pk_bf16_f32 v50, v52, v53
	s_waitcnt lgkmcnt(0)
	v_add_f32_e32 v48, v48, v49
	ds_bpermute_b32 v49, v126, v48
	v_cvt_pk_bf16_f32 v51, v54, v55
	v_cvt_pk_bf16_f32 v52, v62, v63
	v_cvt_pk_bf16_f32 v53, v60, v61
	global_store_dwordx4 v[88:89], v[50:53], off
	s_and_saveexec_b64 s[6:7], vcc
	s_cbranch_execz .LBB0_1002
	s_waitcnt lgkmcnt(0)
	v_add_f32_e32 v48, v48, v49
	ds_write_b32 v124, v48 offset:2048
; __device__ __forceinline__ unsigned cvt_pk_bf16(float lo, float hi) { unsigned r; asm volatile("v_cvt_pk_bf16_f32 %0, %1, %2" : "=v"(r) : "v"(lo), "v"(hi)); return r; }
; #define EPR_LOAD(IT, BUF) do { const unsigned row_ = rb + 128 * ((IT) >> 2) + 16 * ((IT) & 3); _Pragma("unroll") for (int bj = 0; bj < 2; ++bj) \
;             xin[BUF][bj] = *(const u32x4*)(XG + (row_ * DM + cbase + bj * 128)); } while (0)
;     __device__ __forceinline__ void operator()(f32x4 (&acc)[2][2][4][2], const Unit& u, int ui, int wr, int wc, int fr, int fq, int lane, LAS unsigned char* lds) const {
;     ...
;         for (int it = 0; it < 8; ++it) {
;             if (it + 1 < 8) EPR_LOAD(it + 1, (it + 1) & 1);
;             __builtin_amdgcn_sched_barrier(0);
;             const int ai = it >> 2, m = it & 3;
;             const unsigned row = rb + 128 * ai + 16 * m;
;             float ss = 0.f;
; #pragma unroll
;             for (int bj = 0; bj < 2; ++bj) {
;                 const u32x4 xw = xin[it & 1][bj];
;                 f32x4 v0, v1;
;                 v0[0] = __builtin_bit_cast(float, xw.x << 16); v0[1] = __builtin_bit_cast(float, xw.x & 0xffff0000u); v0[2] = __builtin_bit_cast(float, xw.y << 16); v0[3] = __builtin_bit_cast(float, xw.y & 0xffff0000u);
;                 v1[0] = __builtin_bit_cast(float, xw.z << 16); v1[1] = __builtin_bit_cast(float, xw.z & 0xffff0000u); v1[2] = __builtin_bit_cast(float, xw.w << 16); v1[3] = __builtin_bit_cast(float, xw.w & 0xffff0000u);
;                 v0 += acc[ai][bj][m][0]; v1 += acc[ai][bj][m][1];
;                 ss += ((v0[0] * v0[0] + v0[1] * v0[1]) + (v0[2] * v0[2] + v0[3] * v0[3])) + ((v1[0] * v1[0] + v1[1] * v1[1]) + (v1[2] * v1[2] + v1[3] * v1[3]));
;                 u32x4 w; w.x = cvt_pk_bf16(v0[0], v0[1]); w.y = cvt_pk_bf16(v0[2], v0[3]); w.z = cvt_pk_bf16(v1[0], v1[1]); w.w = cvt_pk_bf16(v1[2], v1[3]);
;                 *(u32x4*)(XG + (row * DM + cbase + bj * 128)) = w;
;             }
;             ss += __shfl_xor(ss, 16); ss += __shfl_xor(ss, 32);
;             if (fq == 0) red[(128 * ai + 64 * wr + 16 * m + fr) * 4 + wc] = ss;
.LBB0_1002:
	s_or_b64 exec, exec, s[6:7]
	v_add_u32_e32 v48, 0x28000, v138
	s_waitcnt lgkmcnt(0)
	v_mov_b32_e32 v49, v189
	v_lshl_add_u64 v[58:59], v[48:49], 1, s[10:11]
	v_add_u32_e32 v48, 0x28080, v138
	v_lshl_add_u64 v[56:57], v[48:49], 1, s[10:11]
	s_waitcnt vmcnt(15)
	v_lshlrev_b32_e32 v60, 16, v198
	v_and_b32_e32 v61, 0xffff0000, v198
	v_lshlrev_b32_e32 v62, 16, v199
	v_and_b32_e32 v63, 0xffff0000, v199
	v_lshlrev_b32_e32 v68, 16, v200
	v_and_b32_e32 v69, 0xffff0000, v200
	v_lshlrev_b32_e32 v70, 16, v201
	v_and_b32_e32 v71, 0xffff0000, v201
	v_pk_add_f32 v[46:47], v[46:47], v[62:63]
	v_pk_add_f32 v[44:45], v[44:45], v[60:61]
	v_pk_add_f32 v[60:61], v[42:43], v[70:71]
	v_pk_add_f32 v[42:43], v[40:41], v[68:69]
	v_mul_f32_e32 v40, v45, v45
	v_mul_f32_e32 v41, v47, v47
	v_fmac_f32_e32 v40, v44, v44
	v_fmac_f32_e32 v41, v46, v46
	v_add_f32_e32 v40, v40, v41
	v_mul_f32_e32 v41, v43, v43
	v_mul_f32_e32 v62, v61, v61
	v_fmac_f32_e32 v41, v42, v42
	v_fmac_f32_e32 v62, v60, v60
	v_add_f32_e32 v41, v41, v62
	v_add_f32_e32 v68, v40, v41
	v_cvt_pk_bf16_f32 v40, v44, v45
	v_cvt_pk_bf16_f32 v41, v46, v47
	s_waitcnt vmcnt(14)
	v_lshlrev_b32_e32 v44, 16, v202
	v_and_b32_e32 v45, 0xffff0000, v202
	v_lshlrev_b32_e32 v46, 16, v203
	v_and_b32_e32 v47, 0xffff0000, v203
	v_lshlrev_b32_e32 v62, 16, v204
	v_and_b32_e32 v63, 0xffff0000, v204
	v_pk_add_f32 v[38:39], v[38:39], v[46:47]
	v_pk_add_f32 v[36:37], v[36:37], v[44:45]
	v_lshlrev_b32_e32 v64, 16, v205
	v_and_b32_e32 v65, 0xffff0000, v205
	v_pk_add_f32 v[46:47], v[32:33], v[62:63]
	v_mul_f32_e32 v32, v37, v37
	v_mul_f32_e32 v33, v39, v39
	v_pk_add_f32 v[44:45], v[34:35], v[64:65]
	v_fmac_f32_e32 v32, v36, v36
	v_fmac_f32_e32 v33, v38, v38
	v_add_f32_e32 v32, v32, v33
	v_mul_f32_e32 v33, v47, v47
	v_mul_f32_e32 v34, v45, v45
	v_fmac_f32_e32 v33, v46, v46
	v_fmac_f32_e32 v34, v44, v44
	v_add_f32_e32 v33, v33, v34
	v_add_f32_e32 v32, v32, v33
	v_add_f32_e32 v32, v68, v32
	ds_bpermute_b32 v33, v125, v32
	v_cvt_pk_bf16_f32 v42, v42, v43
	v_cvt_pk_bf16_f32 v43, v60, v61
	global_store_dwordx4 v[74:75], v[40:43], off
	v_cvt_pk_bf16_f32 v34, v36, v37
	s_waitcnt lgkmcnt(0)
	v_add_f32_e32 v32, v32, v33
	ds_bpermute_b32 v33, v126, v32
	v_cvt_pk_bf16_f32 v35, v38, v39
	v_cvt_pk_bf16_f32 v36, v46, v47
	v_cvt_pk_bf16_f32 v37, v44, v45
	global_store_dwordx4 v[72:73], v[34:37], off
	s_and_saveexec_b64 s[6:7], vcc
	s_cbranch_execz .LBB0_1004
	s_waitcnt lgkmcnt(0)
	v_add_f32_e32 v32, v32, v33
	ds_write_b32 v124, v32 offset:2304
; __device__ __forceinline__ unsigned cvt_pk_bf16(float lo, float hi) { unsigned r; asm volatile("v_cvt_pk_bf16_f32 %0, %1, %2" : "=v"(r) : "v"(lo), "v"(hi)); return r; }
; #define EPR_LOAD(IT, BUF) do { const unsigned row_ = rb + 128 * ((IT) >> 2) + 16 * ((IT) & 3); _Pragma("unroll") for (int bj = 0; bj < 2; ++bj) \
;             xin[BUF][bj] = *(const u32x4*)(XG + (row_ * DM + cbase + bj * 128)); } while (0)
;     __device__ __forceinline__ void operator()(f32x4 (&acc)[2][2][4][2], const Unit& u, int ui, int wr, int wc, int fr, int fq, int lane, LAS unsigned char* lds) const {
;     ...
;         for (int it = 0; it < 8; ++it) {
;             if (it + 1 < 8) EPR_LOAD(it + 1, (it + 1) & 1);
;             __builtin_amdgcn_sched_barrier(0);
;             const int ai = it >> 2, m = it & 3;
;             const unsigned row = rb + 128 * ai + 16 * m;
;             float ss = 0.f;
; #pragma unroll
;             for (int bj = 0; bj < 2; ++bj) {
;                 const u32x4 xw = xin[it & 1][bj];
;                 f32x4 v0, v1;
;                 v0[0] = __builtin_bit_cast(float, xw.x << 16); v0[1] = __builtin_bit_cast(float, xw.x & 0xffff0000u); v0[2] = __builtin_bit_cast(float, xw.y << 16); v0[3] = __builtin_bit_cast(float, xw.y & 0xffff0000u);
;                 v1[0] = __builtin_bit_cast(float, xw.z << 16); v1[1] = __builtin_bit_cast(float, xw.z & 0xffff0000u); v1[2] = __builtin_bit_cast(float, xw.w << 16); v1[3] = __builtin_bit_cast(float, xw.w & 0xffff0000u);
;                 v0 += acc[ai][bj][m][0]; v1 += acc[ai][bj][m][1];
;                 ss += ((v0[0] * v0[0] + v0[1] * v0[1]) + (v0[2] * v0[2] + v0[3] * v0[3])) + ((v1[0] * v1[0] + v1[1] * v1[1]) + (v1[2] * v1[2] + v1[3] * v1[3]));
;                 u32x4 w; w.x = cvt_pk_bf16(v0[0], v0[1]); w.y = cvt_pk_bf16(v0[2], v0[3]); w.z = cvt_pk_bf16(v1[0], v1[1]); w.w = cvt_pk_bf16(v1[2], v1[3]);
;                 *(u32x4*)(XG + (row * DM + cbase + bj * 128)) = w;
;             }
;             ss += __shfl_xor(ss, 16); ss += __shfl_xor(ss, 32);
;             if (fq == 0) red[(128 * ai + 64 * wr + 16 * m + fr) * 4 + wc] = ss;
.LBB0_1004:
	s_or_b64 exec, exec, s[6:7]
	v_add_u32_e32 v32, 0x2c000, v138
	s_waitcnt lgkmcnt(0)
	v_mov_b32_e32 v33, v189
	v_lshl_add_u64 v[42:43], v[32:33], 1, s[10:11]
	v_add_u32_e32 v32, 0x2c080, v138
	v_lshl_add_u64 v[40:41], v[32:33], 1, s[10:11]
	s_waitcnt vmcnt(15)
	v_lshlrev_b32_e32 v44, 16, v212
	v_and_b32_e32 v45, 0xffff0000, v212
	v_lshlrev_b32_e32 v46, 16, v213
	v_and_b32_e32 v47, 0xffff0000, v213
	v_lshlrev_b32_e32 v52, 16, v214
	v_and_b32_e32 v53, 0xffff0000, v214
	v_lshlrev_b32_e32 v54, 16, v215
	v_and_b32_e32 v55, 0xffff0000, v215
	v_pk_add_f32 v[30:31], v[30:31], v[46:47]
	v_pk_add_f32 v[28:29], v[28:29], v[44:45]
	v_pk_add_f32 v[44:45], v[26:27], v[54:55]
	v_pk_add_f32 v[26:27], v[24:25], v[52:53]
	v_mul_f32_e32 v24, v29, v29
	v_mul_f32_e32 v25, v31, v31
	v_fmac_f32_e32 v24, v28, v28
	v_fmac_f32_e32 v25, v30, v30
	v_add_f32_e32 v24, v24, v25
	v_mul_f32_e32 v25, v27, v27
	v_mul_f32_e32 v46, v45, v45
	v_fmac_f32_e32 v25, v26, v26
	v_fmac_f32_e32 v46, v44, v44
	v_add_f32_e32 v25, v25, v46
	v_add_f32_e32 v52, v24, v25
	v_cvt_pk_bf16_f32 v24, v28, v29
	v_cvt_pk_bf16_f32 v25, v30, v31
	s_waitcnt vmcnt(14)
	v_lshlrev_b32_e32 v28, 16, v216
	v_and_b32_e32 v29, 0xffff0000, v216
	v_lshlrev_b32_e32 v30, 16, v217
	v_and_b32_e32 v31, 0xffff0000, v217
	v_lshlrev_b32_e32 v46, 16, v218
	v_and_b32_e32 v47, 0xffff0000, v218
	v_pk_add_f32 v[22:23], v[22:23], v[30:31]
	v_pk_add_f32 v[20:21], v[20:21], v[28:29]
	v_lshlrev_b32_e32 v48, 16, v219
	v_and_b32_e32 v49, 0xffff0000, v219
	v_pk_add_f32 v[30:31], v[16:17], v[46:47]
	v_mul_f32_e32 v16, v21, v21
	v_mul_f32_e32 v17, v23, v23
	v_pk_add_f32 v[28:29], v[18:19], v[48:49]
	v_fmac_f32_e32 v16, v20, v20
	v_fmac_f32_e32 v17, v22, v22
	v_add_f32_e32 v16, v16, v17
	v_mul_f32_e32 v17, v31, v31
	v_mul_f32_e32 v18, v29, v29
	v_fmac_f32_e32 v17, v30, v30
	v_fmac_f32_e32 v18, v28, v28
	v_add_f32_e32 v17, v17, v18
	v_add_f32_e32 v16, v16, v17
	v_add_f32_e32 v16, v52, v16
	ds_bpermute_b32 v17, v125, v16
	v_cvt_pk_bf16_f32 v26, v26, v27
	v_cvt_pk_bf16_f32 v27, v44, v45
	global_store_dwordx4 v[58:59], v[24:27], off
	v_cvt_pk_bf16_f32 v18, v20, v21
	s_waitcnt lgkmcnt(0)
	v_add_f32_e32 v16, v16, v17
	ds_bpermute_b32 v17, v126, v16
	v_cvt_pk_bf16_f32 v19, v22, v23
	v_cvt_pk_bf16_f32 v20, v30, v31
	v_cvt_pk_bf16_f32 v21, v28, v29
	global_store_dwordx4 v[56:57], v[18:21], off
	s_and_saveexec_b64 s[6:7], vcc
	s_cbranch_execz .LBB0_1006
	s_waitcnt lgkmcnt(0)
	v_add_f32_e32 v16, v16, v17
	ds_write_b32 v124, v16 offset:2560
.LBB0_1006:
	s_or_b64 exec, exec, s[6:7]
	s_waitcnt vmcnt(15)
	v_lshlrev_b32_e32 v16, 16, v220
	s_waitcnt lgkmcnt(0)
	v_and_b32_e32 v17, 0xffff0000, v220
	v_lshlrev_b32_e32 v18, 16, v221
	v_and_b32_e32 v19, 0xffff0000, v221
	v_lshlrev_b32_e32 v20, 16, v222
	v_and_b32_e32 v21, 0xffff0000, v222
	v_lshlrev_b32_e32 v22, 16, v223
	v_and_b32_e32 v23, 0xffff0000, v223
	v_pk_add_f32 v[14:15], v[14:15], v[18:19]
	v_pk_add_f32 v[12:13], v[12:13], v[16:17]
	v_pk_add_f32 v[16:17], v[10:11], v[22:23]
	v_pk_add_f32 v[10:11], v[8:9], v[20:21]
	v_mul_f32_e32 v8, v13, v13
	v_mul_f32_e32 v9, v15, v15
	v_fmac_f32_e32 v8, v12, v12
	v_fmac_f32_e32 v9, v14, v14
	v_add_f32_e32 v8, v8, v9
	v_mul_f32_e32 v9, v11, v11
	v_mul_f32_e32 v18, v17, v17
	v_fmac_f32_e32 v9, v10, v10
	v_fmac_f32_e32 v18, v16, v16
	v_add_f32_e32 v9, v9, v18
	v_add_f32_e32 v22, v8, v9
	v_cvt_pk_bf16_f32 v8, v12, v13
	v_cvt_pk_bf16_f32 v9, v14, v15
	s_waitcnt vmcnt(14)
	v_lshlrev_b32_e32 v12, 16, v224
	v_and_b32_e32 v13, 0xffff0000, v224
	v_lshlrev_b32_e32 v14, 16, v225
	v_and_b32_e32 v15, 0xffff0000, v225
	v_lshlrev_b32_e32 v18, 16, v226
	v_and_b32_e32 v19, 0xffff0000, v226
	v_pk_add_f32 v[6:7], v[6:7], v[14:15]
	v_pk_add_f32 v[4:5], v[4:5], v[12:13]
	v_lshlrev_b32_e32 v20, 16, v227
	v_and_b32_e32 v21, 0xffff0000, v227
	v_pk_add_f32 v[14:15], v[0:1], v[18:19]
	v_mul_f32_e32 v0, v5, v5
	v_mul_f32_e32 v1, v7, v7
	v_pk_add_f32 v[12:13], v[2:3], v[20:21]
	v_fmac_f32_e32 v0, v4, v4
	v_fmac_f32_e32 v1, v6, v6
	v_add_f32_e32 v0, v0, v1
	v_mul_f32_e32 v1, v15, v15
	v_mul_f32_e32 v2, v13, v13
	v_fmac_f32_e32 v1, v14, v14
	v_fmac_f32_e32 v2, v12, v12
	v_add_f32_e32 v1, v1, v2
	v_add_f32_e32 v0, v0, v1
	v_add_f32_e32 v0, v22, v0
	ds_bpermute_b32 v1, v125, v0
	v_cvt_pk_bf16_f32 v10, v10, v11
	v_cvt_pk_bf16_f32 v11, v16, v17
	global_store_dwordx4 v[42:43], v[8:11], off
	v_cvt_pk_bf16_f32 v2, v4, v5
	s_waitcnt lgkmcnt(0)
	v_add_f32_e32 v0, v0, v1
	ds_bpermute_b32 v1, v126, v0
	v_cvt_pk_bf16_f32 v3, v6, v7
	v_cvt_pk_bf16_f32 v4, v14, v15
	v_cvt_pk_bf16_f32 v5, v12, v13
	global_store_dwordx4 v[40:41], v[2:5], off
	s_and_saveexec_b64 s[6:7], vcc
	s_cbranch_execz .LBB0_1008
	s_waitcnt lgkmcnt(0)
	v_add_f32_e32 v0, v0, v1
	ds_write_b32 v124, v0 offset:2816
